# attnA+B: one barrier per tile, LDS writes interleaved, counted lgkmcnt waits, K-frag prefetch, VALU trims
# speedup vs baseline: 1.0148x; 1.0148x over previous
;     ...
;   const int wid = tid >> 6, lane = tid & 63, r32 = lane & 31, hi = lane >> 5;
;   char* V_lds = lds; char* K_lds = lds + 2 * SHM_V;
;   float* ws = (float*)(lds + CF::WS_OFF) + wid * 64; float* li_l = ws; float* al_l = ws + 32;
;   float m_reg = -1e30f, l_reg = 0; f32x16 o[4] = {}; bf16x8 qr[8];
;   const bf16_t* Qw = a.Q + (long)(wid * QBLK + r32) * ldq + hi * 8;
; #pragma unroll
;   for (int d0 = 0; d0 < CF::NQR; ++d0) qr[d0] = ld8(Qw + d0 * 16);
;   char* const qx = lds + CF::QX_OFF + wid * CF::QXW + lane * 16;
;   if constexpr (ND0 > 8) {
; #pragma unroll
;     for (int d0 = CF::NQR; d0 < ND0; ++d0) *(bf16x8*)(qx + (d0 - CF::NQR) * 1024) = ld8(Qw + d0 * 16);
;   }
;   const int sr = tid >> 4, sc = (tid & 15) * 8, vst0 = v_st(sr, sc), vst1 = v_st(32 + sr, sc);
;   const int kst0 = sr * CF::KPITCH + ((sc * 2) ^ ((sr & CF::KSWM) << 4)), kst1 = kst0 + 32 * CF::KPITCH;
;   const int kr2 = tid >> 3, kst2 = kr2 * CF::KPITCH + ((256 + (tid & 7) * 16) ^ ((kr2 & 7) << 4));
;   const bf16_t* const Vg = a.V; const bf16_t* const Kg = a.K;
;   const int voff0 = sr * ldv + sc, koff0 = sr * ldk + sc, koff2 = kr2 * ldk + 128 + (tid & 7) * 8;
;   const int vb0 = (int)(uintptr_t)V_lds + v_rd_base(lane);
;   struct { bf16x8 vs0, vs1, ks0, ks1, ks2; } sr_[SDEPTH];
;     ...
;   f32x16 pA0, pA1, pB0, pB1; float mnA, mnB, alA, alB; bf16x8 pa0, pa1, pa2, pa3; const int NT = a.nt;
; __global__ void __launch_bounds__(NWAVES * 64, 2) mk_fwd(Args args) {
;     ...
;                   for (int i = 0; i < nu; ++i) { PHASE_VARS(); CHUNK_VARS(); bf16* const QKV = (bf16*)(BIG + A_QKV); bf16* const OB = (bf16*)(BIG + A_O);
;                       const int U8 = g8 ? (CT / 256) * 16 / 8 : (CT / 256) * 16, UPG = 4 * NQB; if (r8 + G8 * i >= U8) break;
;                       const int u = x8 * U8 + r8 + G8 * i, grp = u / UPG, w = u % UPG, s = grp >> 2, kvh = grp & 3, h = kvh * 4 + w / NQB, qb = w % NQB;
;                       const size_t t0 = (size_t)s * SEQ, tq = t0 + (size_t)qb * 256;
;                       att::Unit un; un.Q = QKV + tq * 3072 + h * 128; un.K = QKV + t0 * 3072 + 2048 + kvh * 128; un.V = un.K + 512; un.O = OB + tq * DM + h * 128; un.LSE = nullptr;
;                       un.ldq = 3072; un.ldk = 3072; un.ldv = 3072; un.ldo = DM; un.ldl = 0; un.nt = SEQ / 64; un.qoff = 0;
;                       ATT_A_FN<CfgA, false, false, 3072, 3072, 3072, DM>(un, (char*)lds_raw, tid); } }
.LBB0_799:
	s_mov_b32 s11, 0
	v_mbcnt_lo_u32_b32 v0, -1, 0
	v_mbcnt_hi_u32_b32 v0, -1, v0
	s_add_i32 s0, s11, s2
	s_ashr_i32 s5, s0, 31
	s_lshr_b32 s5, s5, 29
	s_add_i32 s8, s11, s1
	s_add_i32 s5, s0, s5
	s_and_b32 s4, s8, 7
	s_ashr_i32 s9, s5, 3
	s_ashr_i32 s10, s8, 3
	s_cmp_eq_u32 s4, 0
	s_cselect_b64 s[4:5], -1, 0
	s_and_b64 s[6:7], s[4:5], exec
	s_cselect_b32 s7, s10, s8
	s_movk_i32 s8, 0x800
	s_cselect_b32 s6, s9, s0
	s_cselect_b32 s10, 0x100, s8
	s_mul_i32 s8, s7, s17
	s_add_i32 s8, s8, s6
	s_cmp_ge_i32 s8, s10
	s_mov_b64 s[6:7], -1
	s_cbranch_scc1 .LBB0_798
	s_lshl_b32 s6, s9, 3
	s_sub_i32 s0, s0, s6
	s_and_b64 s[6:7], s[4:5], exec
	s_cselect_b32 s6, s0, 0
	s_sub_i32 s0, 0, s11
	s_cmp_eq_u32 s38, s0
	s_movk_i32 s25, 0x1000
	s_cselect_b32 s0, s25, 0x2000
	s_cselect_b32 s9, 12, 13
	s_lshr_b32 s7, s0, 8
	s_lshr_b32 s0, s0, 6
	s_ashr_i32 s12, s11, 31
	s_add_u32 s19, s58, s11
	s_addc_u32 s18, s59, s12
	s_add_u32 s22, s19, 0x2a800000
	s_addc_u32 s23, s18, 0
	s_and_b64 s[4:5], s[4:5], exec
	s_cselect_b32 s4, 8, 11
	s_lshl_b32 s4, s6, s4
	s_abs_i32 s6, s0
	v_cvt_f32_u32_e32 v2, s6
	s_sub_i32 s10, 0, s6
	s_add_i32 s8, s8, s4
	s_abs_i32 s5, s8
	v_rcp_iflag_f32_e32 v2, v2
	s_xor_b32 s4, s8, s0
	s_ashr_i32 s4, s4, 31
	v_add_u32_e32 v1, s3, v0
	v_mul_f32_e32 v2, 0x4f7ffffe, v2
	v_cvt_u32_f32_e32 v2, v2
	v_ashrrev_i32_e32 v215, 6, v1
	v_and_b32_e32 v53, 31, v0
	v_lshlrev_b32_e32 v214, 5, v215
	v_readfirstlane_b32 s13, v2
	s_mul_i32 s10, s10, s13
	s_mul_hi_u32 s10, s13, s10
	s_add_i32 s13, s13, s10
	s_mul_hi_u32 s10, s5, s13
	s_mul_i32 s13, s10, s6
	s_sub_i32 s5, s5, s13
	s_add_i32 s13, s10, 1
	s_sub_i32 s14, s5, s6
	s_cmp_ge_u32 s5, s6
	s_cselect_b32 s10, s13, s10
	s_cselect_b32 s5, s14, s5
	s_add_i32 s13, s10, 1
	s_cmp_ge_u32 s5, s6
	s_cselect_b32 s5, s13, s10
	s_sext_i32_i8 s14, s7
	s_xor_b32 s5, s5, s4
	v_cvt_f32_i32_e32 v3, s14
	s_sub_i32 s13, s5, s4
	s_mul_i32 s4, s13, s0
	s_sub_i32 s8, s8, s4
	v_cvt_f32_i32_e32 v2, s8
	v_rcp_iflag_f32_e32 v4, v3
	s_ashr_i32 s6, s13, 2
	s_and_b32 s24, s13, 3
	s_xor_b32 s13, s8, s14
	v_mul_f32_e32 v4, v2, v4
	v_trunc_f32_e32 v4, v4
	v_fma_f32 v2, -v4, v3, v2
	v_cvt_i32_f32_e32 v4, v4
	s_ashr_i32 s13, s13, 30
	v_cmp_ge_f32_e64 s[4:5], |v2|, |v3|
	s_or_b32 s13, s13, 1
	s_and_b64 s[4:5], s[4:5], exec
	s_cselect_b32 s4, s13, 0
	v_readfirstlane_b32 s5, v4
	s_add_i32 s4, s5, s4
	s_sext_i32_i8 s13, s4
	s_mul_i32 s4, s4, s7
	s_sub_i32 s4, s8, s4
	s_ashr_i32 s7, s6, 31
	s_bfe_i64 s[4:5], s[4:5], 0x80000
	s_lshl_b64 s[14:15], s[6:7], s9
	s_lshl_b64 s[4:5], s[4:5], 8
	s_add_u32 s6, s4, s14
	s_addc_u32 s7, s5, s15
	s_mul_i32 s4, s7, 0x1800
	s_mul_hi_u32 s5, s6, 0x1800
	s_add_i32 s5, s5, s4
	s_mul_i32 s4, s6, 0x1800
	s_add_u32 s20, s22, s4
	s_addc_u32 s21, s23, s5
	s_lshl_b32 s4, s24, 9
	s_lshl_b32 s5, s13, 7
	s_add_i32 s4, s5, s4
	s_ashr_i32 s5, s4, 31
	s_lshl_b64 s[8:9], s[4:5], 1
	s_add_u32 s20, s20, s8
	s_mul_i32 s4, s15, 0x1800
	s_mul_hi_u32 s13, s14, 0x1800
	s_addc_u32 s21, s21, s9
	s_add_i32 s13, s13, s4
	s_mulk_i32 s14, 0x1800
	s_add_u32 s4, s22, s14
	s_addc_u32 s5, s23, s13
	s_lshl_b32 s15, s24, 8
	s_add_u32 s4, s4, s15
	s_addc_u32 s5, s5, 0
	v_and_b32_e32 v2, 0x3fffffc0, v1
	s_add_i32 s22, 0, 0x11000
	v_lshl_add_u32 v223, v2, 2, s22
	v_or_b32_e32 v4, v214, v53
	v_mov_b64_e32 v[2:3], s[20:21]
	v_lshrrev_b32_e32 v16, 1, v0
	v_mad_i64_i32 v[2:3], s[20:21], v4, s96, v[2:3]
	v_and_b32_e32 v204, 16, v16
	v_lshl_add_u64 v[2:3], v[2:3], 0, v[204:205]
	global_load_dwordx4 v[156:159], v[2:3], off
	global_load_dwordx4 v[152:155], v[2:3], off offset:32
	global_load_dwordx4 v[148:151], v[2:3], off offset:64
	global_load_dwordx4 v[144:147], v[2:3], off offset:96
	global_load_dwordx4 v[140:143], v[2:3], off offset:128
	global_load_dwordx4 v[136:139], v[2:3], off offset:160
	global_load_dwordx4 v[132:135], v[2:3], off offset:192
	global_load_dwordx4 v[128:131], v[2:3], off offset:224
	v_ashrrev_i32_e32 v2, 4, v1
	v_and_b32_e32 v5, 0xfffff0, v2
	v_lshlrev_b32_e32 v6, 1, v2
	v_lshlrev_b32_e32 v3, 3, v0
	v_and_or_b32 v5, v6, 8, v5
	v_and_b32_e32 v4, 0x78, v3
	v_lshrrev_b32_e32 v6, 1, v2
	v_lshrrev_b32_e32 v5, 1, v5
	v_bfe_u32 v3, v3, 5, 2
	v_and_b32_e32 v7, 3, v2
	v_or_b32_e32 v5, v5, v3
	v_and_or_b32 v6, v6, 4, v7
	v_lshlrev_b32_e32 v7, 1, v4
	v_lshlrev_b32_e32 v5, 9, v5
	v_lshlrev_b32_e32 v6, 6, v6
	v_and_b32_e32 v8, 48, v7
	v_or3_b32 v17, v5, v6, v8
	v_add_u32_e32 v5, 32, v2
	v_and_b32_e32 v9, 0xfffff0, v5
	v_lshlrev_b32_e32 v5, 1, v5
	v_and_or_b32 v5, v5, 8, v9
	v_lshrrev_b32_e32 v5, 1, v5
	v_or_b32_e32 v3, v5, v3
	v_lshlrev_b32_e32 v3, 9, v3
	v_or3_b32 v18, v3, v6, v8
	v_lshlrev_b32_e32 v3, 8, v2
	v_and_b32_e32 v1, 0x70, v1
	s_movk_i32 s20, 0xc00
	v_and_b32_e32 v52, 63, v0
	v_bitop3_b32 v19, v7, v3, v1 bitop3:0xde
	v_mul_lo_u32 v1, v2, s20
	v_lshlrev_b32_e32 v20, 4, v0
	v_or_b32_e32 v2, v1, v4
	v_lshlrev_b32_e32 v1, 3, v52
	v_and_b32_e32 v3, 0xc0, v20
	v_lshlrev_b32_e32 v0, 1, v0
	v_and_or_b32 v3, v1, 24, v3
	v_and_b32_e32 v0, 32, v0
	v_and_b32_e32 v1, 0x100, v1
	v_or3_b32 v54, v3, v0, v1
	v_ashrrev_i32_e32 v3, 31, v2
	v_lshlrev_b64 v[48:49], 1, v[2:3]
	v_lshl_add_u64 v[50:51], s[4:5], 0, v[48:49]
	s_mov_b64 s[4:5], 0x1000
	v_lshl_add_u64 v[0:1], v[50:51], 0, s[4:5]
	s_mov_b32 s4, 0x31000
	v_add_co_u32_e32 v12, vcc, s4, v50
	global_load_dwordx4 v[0:3], v[0:1], off offset:1024
	s_nop 0
	v_addc_co_u32_e32 v13, vcc, 0, v51, vcc
	v_add_co_u32_e32 v8, vcc, s25, v50
	global_load_dwordx4 v[4:7], v[12:13], off offset:1024
	s_nop 0
	v_addc_co_u32_e32 v9, vcc, 0, v51, vcc
	global_load_dwordx4 v[8:11], v[8:9], off
	s_nop 0
	global_load_dwordx4 v[12:15], v[12:13], off
	v_add_u32_e32 v226, 0, v17
	v_and_b32_e32 v64, 0x70, v20
	s_waitcnt vmcnt(0)
	v_lshl_add_u32 v55, v53, 8, 0
	v_add_u32_e32 v227, 0, v18
	v_add_u32_e32 v228, 0, v19
	v_bitop3_b32 v56, v204, v64, 32 bitop3:0x36
	v_add_u32_e32 v236, v55, v56
	s_movk_i32 s4, 0x60
	s_cmp_lg_u32 0, -1
	s_cselect_b32 s20, 0, 0
	v_add_u32_e32 v224, s20, v54
	s_mov_b32 s40, s41
	s_mov_b32 s42, s41
	s_mov_b32 s43, s41
	s_mov_b32 s44, s41
	s_mov_b32 s45, s41
	s_mov_b32 s46, s41
	s_mov_b32 s47, s41
	s_mov_b32 s48, s41
	s_mov_b32 s49, s41
	s_mov_b32 s50, s41
	s_mov_b32 s51, s41
	s_mov_b32 s52, s41
	s_mov_b32 s53, s41
	s_mov_b32 s54, s41
	s_mov_b32 s55, s41
	v_lshl_add_u32 v237, v53, 2, v223
	v_mov_b32_e32 v222, 0x358637bd
	v_bfrev_b32_e32 v254, 0.5
	s_mov_b32 s10, 2
	s_movk_i32 s81, 0x1000
	v_mov_b32_e32 v240, 0
	s_waitcnt vmcnt(0)
	ds_write_b128 v226, v[0:3]
	v_bitop3_b32 v0, v16, v64, 16 bitop3:0x6c
	v_add_u32_e32 v229, v55, v0
	ds_write_b128 v227, v[4:7]
	ds_write_b128 v228, v[8:11] offset:32768
	ds_write_b128 v228, v[12:15] offset:40960
	s_waitcnt lgkmcnt(0)
	s_barrier
; template <class CF> __device__ __forceinline__ void qkt(f32x16& p0, f32x16& p1, const char* Ks, const bf16x8* qr, const char* qx, int r32, int hi) {
;   p0 = f32x16{}; p1 = f32x16{};
; #pragma unroll
;   for (int d0 = 0; d0 < CF::ND0; ++d0) { const int cb = (d0 * 16 + hi * 8) * 2;
;     bf16x8 b0 = *reinterpret_cast<const bf16x8*>(Ks + (r32) * CF::KPITCH + (cb ^ ((r32 & CF::KSWM) << 4)));
;     bf16x8 b1 = *reinterpret_cast<const bf16x8*>(Ks + (32 + r32) * CF::KPITCH + (cb ^ ((r32 & CF::KSWM) << 4)));
;     bf16x8 q; if (d0 < CF::NQR) q = qr[d0 < CF::NQR ? d0 : 0]; else q = *reinterpret_cast<const bf16x8*>(qx + (d0 - CF::NQR) * 1024);
;     p0 = __builtin_amdgcn_mfma_f32_32x32x16_bf16(b0, q, p0, 0, 0, 0);
;     p1 = __builtin_amdgcn_mfma_f32_32x32x16_bf16(b1, q, p1, 0, 0, 0); }
; }
;     ...
;   float m_reg = -1e30f, l_reg = 0; f32x16 o[4] = {}; bf16x8 qr[8];
	ds_read_b128 v[16:19], v229 offset:32768
	ds_read_b128 v[20:23], v229 offset:40960
	s_waitcnt lgkmcnt(1)
	v_mfma_f32_32x32x16_bf16 v[32:47], v[16:19], v[156:159], 0
	ds_read_b128 v[56:59], v236 offset:32768
	ds_read_b128 v[60:63], v236 offset:40960
	v_mov_b64_e32 v[0:1], s[40:41]
	v_mov_b64_e32 v[14:15], s[54:55]
	v_mov_b64_e32 v[2:3], s[42:43]
	v_mov_b64_e32 v[4:5], s[44:45]
	v_mov_b64_e32 v[6:7], s[46:47]
	v_mov_b64_e32 v[8:9], s[48:49]
	s_waitcnt lgkmcnt(2)
	v_mfma_f32_32x32x16_bf16 v[16:31], v[20:23], v[156:159], 0
	v_mov_b64_e32 v[10:11], s[50:51]
	v_mov_b64_e32 v[12:13], s[52:53]
	s_waitcnt lgkmcnt(1)
	v_mfma_f32_32x32x16_bf16 v[32:47], v[56:59], v[152:155], v[32:47]
	v_bitop3_b32 v56, v204, v64, 64 bitop3:0x36
	v_add_u32_e32 v231, v55, v56
	s_waitcnt lgkmcnt(0)
	v_mfma_f32_32x32x16_bf16 v[16:31], v[60:63], v[152:155], v[16:31]
	ds_read_b128 v[56:59], v231 offset:32768
	ds_read_b128 v[60:63], v231 offset:40960
	s_waitcnt lgkmcnt(1)
	v_mfma_f32_32x32x16_bf16 v[32:47], v[56:59], v[148:151], v[32:47]
	v_bitop3_b32 v56, v204, v64, s4 bitop3:0x36
	v_add_u32_e32 v232, v55, v56
	s_movk_i32 s4, 0xa0
	s_waitcnt lgkmcnt(0)
	v_mfma_f32_32x32x16_bf16 v[16:31], v[60:63], v[148:151], v[16:31]
	ds_read_b128 v[56:59], v232 offset:32768
	ds_read_b128 v[60:63], v232 offset:40960
	s_waitcnt lgkmcnt(1)
	v_mfma_f32_32x32x16_bf16 v[32:47], v[56:59], v[144:147], v[32:47]
	v_bitop3_b32 v56, v204, v64, s97 bitop3:0x36
	v_add_u32_e32 v233, v55, v56
	s_waitcnt lgkmcnt(0)
	v_mfma_f32_32x32x16_bf16 v[16:31], v[60:63], v[144:147], v[16:31]
	ds_read_b128 v[56:59], v233 offset:32768
	ds_read_b128 v[60:63], v233 offset:40960
	s_waitcnt lgkmcnt(1)
	v_mfma_f32_32x32x16_bf16 v[32:47], v[56:59], v[140:143], v[32:47]
	v_bitop3_b32 v56, v204, v64, s4 bitop3:0x36
	v_add_u32_e32 v234, v55, v56
	s_movk_i32 s4, 0xc0
	s_waitcnt lgkmcnt(0)
	v_mfma_f32_32x32x16_bf16 v[16:31], v[60:63], v[140:143], v[16:31]
	ds_read_b128 v[56:59], v234 offset:32768
	ds_read_b128 v[60:63], v234 offset:40960
	s_waitcnt lgkmcnt(1)
	v_mfma_f32_32x32x16_bf16 v[32:47], v[56:59], v[136:139], v[32:47]
	v_bitop3_b32 v56, v204, v64, s4 bitop3:0x36
	v_add_u32_e32 v230, v55, v56
	s_movk_i32 s4, 0xe0
	s_waitcnt lgkmcnt(0)
	v_mfma_f32_32x32x16_bf16 v[16:31], v[60:63], v[136:139], v[16:31]
	ds_read_b128 v[56:59], v230 offset:32768
	ds_read_b128 v[60:63], v230 offset:40960
	s_waitcnt lgkmcnt(1)
	v_mfma_f32_32x32x16_bf16 v[32:47], v[56:59], v[132:135], v[32:47]
	v_bitop3_b32 v56, v204, v64, s4 bitop3:0x36
	v_add_u32_e32 v235, v55, v56
	s_mov_b32 s4, 0x61000
	s_waitcnt lgkmcnt(0)
	v_mfma_f32_32x32x16_bf16 v[16:31], v[60:63], v[132:135], v[16:31]
	ds_read_b128 v[56:59], v235 offset:32768
	ds_read_b128 v[60:63], v235 offset:40960
	s_waitcnt lgkmcnt(1)
	v_mfma_f32_32x32x16_bf16 v[32:47], v[56:59], v[128:131], v[32:47]
	v_mov_b32_e32 v57, 0xf149f2ca
	s_waitcnt lgkmcnt(0)
; #define ATT_SYNC() __syncthreads()
; #define ATT_SLOAD(i, k0) do { const bf16_t* vt_ = Vg + (long)(k0) * ldv; const bf16_t* kt_ = Kg + (long)(k0) * ldk; \
;     sr_[i].vs0 = ld8(vt_ + voff0); sr_[i].vs1 = ld8(vt_ + 32 * ldv + voff0); \
;     sr_[i].ks0 = ld8(kt_ + koff0); sr_[i].ks1 = ld8(kt_ + 32 * ldk + koff0); if constexpr (ND0 == 12) sr_[i].ks2 = ld8(kt_ + koff2); } while (0)
; #define ATT_SWRITE(b, i) do { *(bf16x8*)(V_lds + (b) * SHM_V + vst0) = sr_[i].vs0; *(bf16x8*)(V_lds + (b) * SHM_V + vst1) = sr_[i].vs1; \
;     *(bf16x8*)(K_lds + (b) * SHM_K + kst0) = sr_[i].ks0; *(bf16x8*)(K_lds + (b) * SHM_K + kst1) = sr_[i].ks1; if constexpr (ND0 == 12) *(bf16x8*)(K_lds + (b) * SHM_K + kst2) = sr_[i].ks2; } while (0)
; #define ATT_SWAIT() do { if constexpr (SDEPTH == 2) { if constexpr (ND0 == 12) asm volatile("s_waitcnt vmcnt(5)" ::: "memory"); else asm volatile("s_waitcnt vmcnt(4)" ::: "memory"); } else asm volatile("s_waitcnt vmcnt(0)" ::: "memory"); } while (0)
; template <class CF> __device__ __forceinline__ void partialSM(f32x16& p0, f32x16& p1, float& m_reg, float& mn, float& alpha) {
;   constexpr float C = CF::SCALE * 1.4426950408889634f;
;   float pmax = p0[0];
; #pragma unroll
;   for (int r = 1; r < 16; ++r) pmax = fmaxf(pmax, p0[r]);
; #pragma unroll
;   for (int r = 0; r < 16; ++r) pmax = fmaxf(pmax, p1[r]);
;   { auto rr = __builtin_amdgcn_permlane32_swap(__float_as_uint(pmax), __float_as_uint(pmax), false, false);
;     pmax = fmaxf(__uint_as_float(rr[0]), __uint_as_float(rr[1])); }
;   if (__builtin_expect(__all(pmax - m_reg <= THR / CF::SCALE), 1)) { mn = m_reg; alpha = 1.f; }
;   else { mn = fmaxf(m_reg, pmax); alpha = __builtin_amdgcn_exp2f((m_reg - mn) * C); m_reg = mn; }
;   float mnC = -mn * C;
; #pragma unroll
;   for (int r = 0; r < 16; ++r) p0[r] = fmaf(p0[r], C, mnC);
; #pragma unroll
;   for (int r = 0; r < 16; ++r) p1[r] = fmaf(p1[r], C, mnC);
; #pragma unroll
;   for (int r = 0; r < 16; ++r) p0[r] = __builtin_amdgcn_exp2f(p0[r]);
; }
;     ...
;   qkt<CF>(pA0, pA1, K_lds, qr, qx, r32, hi); if constexpr (MASK) bandmask(pA0, pA1, 0, qi, hi); partialSM<CF>(pA0, pA1, m_reg, mnA, alA);
;   ATT_SLOAD(SO, KVBLK); if constexpr (SDEPTH == 2) { if (2 < NT) ATT_SLOAD(SE, 2 * KVBLK); }
;   ATT_SWAIT(); ATT_SWRITE(1, SO); ATT_SYNC();
	v_mfma_f32_32x32x16_bf16 v[16:31], v[60:63], v[128:131], v[16:31]
	s_nop 8
	v_max_f32_e32 v55, v33, v33
	v_max_f32_e32 v56, v32, v32
	v_max_f32_e32 v55, v56, v55
	v_max3_f32 v55, v55, v34, v35
	v_max3_f32 v55, v55, v36, v37
	v_max3_f32 v55, v55, v38, v39
	v_max3_f32 v55, v55, v40, v41
	v_max3_f32 v55, v55, v42, v43
	v_max3_f32 v55, v55, v44, v45
	v_max3_f32 v55, v55, v46, v47
	v_max3_f32 v55, v55, v16, v17
	v_max3_f32 v55, v55, v18, v19
	v_max3_f32 v55, v55, v20, v21
	v_max3_f32 v55, v55, v22, v23
	v_max3_f32 v55, v55, v24, v25
	v_max3_f32 v55, v55, v26, v27
	v_max3_f32 v55, v55, v28, v29
	v_max3_f32 v55, v55, v30, v31
	v_mov_b32_e32 v56, v55
	s_nop 1
	v_permlane32_swap_b32_e32 v55, v56
	v_max_f32_e32 v56, v56, v56
	v_max_f32_e32 v55, v55, v55
	v_max_f32_e32 v55, v55, v56
	v_add_f32_e32 v56, 0x7149f2ca, v55
	v_max_f32_e32 v55, 0xf149f2ca, v55
	v_cmp_ge_f32_e32 vcc, s66, v56
	v_sub_f32_e32 v56, 0xf149f2ca, v55
	v_mul_f32_e32 v56, 0x3e0293ee, v56
	v_exp_f32_e32 v56, v56
	s_cmp_eq_u64 vcc, exec
	s_cselect_b64 vcc, -1, 0
	v_cndmask_b32_e32 v238, v55, v57, vcc
	v_cndmask_b32_e64 v239, v56, 1.0, vcc
	v_mul_f32_e32 v56, 0xbe0293ee, v238
	v_pk_fma_f32 v[88:89], v[24:25], s[74:75], v[56:57] op_sel_hi:[1,0,0]
	v_add_co_u32_e32 v24, vcc, s4, v50
	s_mov_b32 s4, 0x91000
	s_nop 0
	v_addc_co_u32_e32 v25, vcc, 0, v51, vcc
	v_pk_fma_f32 v[92:93], v[28:29], s[74:75], v[56:57] op_sel_hi:[1,0,0]
	v_add_co_u32_e32 v28, vcc, s4, v50
	v_fmamk_f32 v32, v32, 0x3e0293ee, v56
	s_nop 0
	v_addc_co_u32_e32 v29, vcc, 0, v51, vcc
	s_mov_b32 s4, 0xc1000
	v_fmamk_f32 v33, v33, 0x3e0293ee, v56
	v_exp_f32_e32 v64, v32
	v_add_co_u32_e32 v32, vcc, s4, v50
	v_fmamk_f32 v34, v34, 0x3e0293ee, v56
	v_exp_f32_e32 v65, v33
	v_addc_co_u32_e32 v33, vcc, 0, v51, vcc
	s_mov_b32 s4, 0xf1000
	v_fmamk_f32 v35, v35, 0x3e0293ee, v56
	v_exp_f32_e32 v66, v34
	v_add_co_u32_e32 v34, vcc, s4, v50
	v_pk_fma_f32 v[94:95], v[30:31], s[74:75], v[56:57] op_sel_hi:[1,0,0]
	v_pk_fma_f32 v[90:91], v[26:27], s[74:75], v[56:57] op_sel_hi:[1,0,0]
	v_pk_fma_f32 v[86:87], v[22:23], s[74:75], v[56:57] op_sel_hi:[1,0,0]
	v_pk_fma_f32 v[84:85], v[20:21], s[74:75], v[56:57] op_sel_hi:[1,0,0]
	v_pk_fma_f32 v[82:83], v[18:19], s[74:75], v[56:57] op_sel_hi:[1,0,0]
	v_pk_fma_f32 v[80:81], v[16:17], s[74:75], v[56:57] op_sel_hi:[1,0,0]
	v_exp_f32_e32 v67, v35
	global_load_dwordx4 v[16:19], v[24:25], off offset:1024
	global_load_dwordx4 v[20:23], v[28:29], off offset:1024
	s_nop 0
	global_load_dwordx4 v[24:27], v[24:25], off
	s_nop 0
	global_load_dwordx4 v[28:31], v[28:29], off
	v_addc_co_u32_e32 v35, vcc, 0, v51, vcc
	global_load_dwordx4 v[160:163], v[32:33], off offset:1024
	global_load_dwordx4 v[164:167], v[34:35], off offset:1024
	global_load_dwordx4 v[168:171], v[32:33], off
	global_load_dwordx4 v[172:175], v[34:35], off
	s_addk_i32 s20, 0x4000
	s_or_b32 s14, s14, s15
	v_readlane_b32 s15, v255, 10
	v_mov_b32_e32 v55, v56
	s_add_u32 s11, s15, s11
	v_readlane_b32 s15, v255, 11
	v_fmamk_f32 v36, v36, 0x3e0293ee, v56
	v_fmamk_f32 v37, v37, 0x3e0293ee, v56
	v_fmamk_f32 v38, v38, 0x3e0293ee, v56
	v_fmamk_f32 v39, v39, 0x3e0293ee, v56
	v_fmamk_f32 v40, v40, 0x3e0293ee, v56
	v_fmamk_f32 v41, v41, 0x3e0293ee, v56
	v_fmamk_f32 v42, v42, 0x3e0293ee, v56
	v_fmamk_f32 v43, v43, 0x3e0293ee, v56
	v_fmamk_f32 v44, v44, 0x3e0293ee, v56
	v_fmamk_f32 v45, v45, 0x3e0293ee, v56
	v_fmamk_f32 v46, v46, 0x3e0293ee, v56
	v_fmac_f32_e32 v55, 0x3e0293ee, v47
	s_addc_u32 s15, s15, s12
	v_exp_f32_e32 v68, v36
	v_exp_f32_e32 v69, v37
	v_exp_f32_e32 v70, v38
	v_exp_f32_e32 v71, v39
	v_exp_f32_e32 v72, v40
	v_exp_f32_e32 v73, v41
	v_exp_f32_e32 v74, v42
	v_exp_f32_e32 v75, v43
	v_exp_f32_e32 v76, v44
	v_exp_f32_e32 v77, v45
	v_exp_f32_e32 v78, v46
	v_exp_f32_e32 v79, v55
	s_add_u32 s12, s11, s14
	s_waitcnt vmcnt(4)
	s_addc_u32 s13, s15, s13
	s_waitcnt vmcnt(7)
	ds_write_b128 v226, v[16:19] offset:16384
	s_waitcnt vmcnt(6)
	ds_write_b128 v227, v[20:23] offset:16384
	s_waitcnt vmcnt(5)
	ds_write_b128 v228, v[24:27] offset:49152
	s_waitcnt vmcnt(4)
	ds_write_b128 v228, v[28:31] offset:57344
	v_cmp_gt_u32_e64 s[4:5], 32, v52
	v_add_u32_e32 v225, s20, v54
	v_lshl_add_u64 v[216:217], s[12:13], 0, v[48:49]
	v_mov_b64_e32 v[62:63], v[14:15]
	v_mov_b64_e32 v[46:47], v[14:15]
	v_mov_b64_e32 v[30:31], v[14:15]
	v_mov_b64_e32 v[60:61], v[12:13]
	v_mov_b64_e32 v[58:59], v[10:11]
	v_mov_b64_e32 v[56:57], v[8:9]
	v_mov_b64_e32 v[54:55], v[6:7]
	v_mov_b64_e32 v[52:53], v[4:5]
	v_mov_b64_e32 v[50:51], v[2:3]
	v_mov_b64_e32 v[48:49], v[0:1]
	v_mov_b64_e32 v[44:45], v[12:13]
	v_mov_b64_e32 v[42:43], v[10:11]
	v_mov_b64_e32 v[40:41], v[8:9]
	v_mov_b64_e32 v[38:39], v[6:7]
	v_mov_b64_e32 v[36:37], v[4:5]
	v_mov_b64_e32 v[34:35], v[2:3]
	v_mov_b64_e32 v[32:33], v[0:1]
	v_mov_b64_e32 v[28:29], v[12:13]
	v_mov_b64_e32 v[26:27], v[10:11]
	v_mov_b64_e32 v[24:25], v[8:9]
	v_mov_b64_e32 v[22:23], v[6:7]
	v_mov_b64_e32 v[20:21], v[4:5]
	v_mov_b64_e32 v[18:19], v[2:3]
	v_mov_b64_e32 v[16:17], v[0:1]
	s_waitcnt lgkmcnt(0)
	s_barrier
	ds_read_b128 v[206:209], v229 offset:49152
	ds_read_b128 v[210:213], v229 offset:57344
	ds_read_b128 v[218:221], v236 offset:49152
	ds_read_b128 v[250:253], v236 offset:57344
	s_branch .LBB0_803

; #define ATT_SBAR() __builtin_amdgcn_sched_barrier(0)
; template <class CF> __device__ __forceinline__ void qk_sm(f32x16& n0, f32x16& n1, const char* Ks, const bf16x8* qr, int r32, int hi,
;                                                           f32x16& p0, f32x16& p1, float alpha, float& l_reg, bf16x8& pa0, bf16x8& pa1, bf16x8& pa2, bf16x8& pa3) {
;   n0 = f32x16{}; n1 = f32x16{};
;   const char* kr = Ks + r32 * CF::KPITCH; const int sw = (r32 & CF::KSWM) << 4;
;   bf16x8 ka[4], kb[4];
;     ...
;   ATT_QRD(ka, 0); ATT_QRD(kb, 1); asm volatile("s_waitcnt lgkmcnt(4)" ::: "memory"); ATT_SBAR();
;     ...
;   ATT_QRD(ka, 0); asm volatile("s_waitcnt lgkmcnt(0)" ::: "memory"); ATT_SBAR();
;     ...
;   ATT_QEARLY(kb, 1);
; #pragma unroll
;   for (int r = 0; r < 16; ++r) p1[r] = __builtin_amdgcn_exp2f(p1[r]);
;   asm volatile("" : "+v"(p1));
;   ATT_QMM(ka, 0);
;     ...
;   ATT_QRD(ka, 2); asm volatile("s_waitcnt lgkmcnt(4)" ::: "memory"); ATT_SBAR();
;     ...
;   asm volatile("s_waitcnt lgkmcnt(0)" ::: "memory"); ATT_SBAR();
;     ...
;   ATT_QEARLY(ka, 2);
;   float ps = 0;
; #pragma unroll
;   for (int r = 0; r < 16; ++r) ps += p0[r];
; #pragma unroll
;   for (int r = 0; r < 16; ++r) ps += p1[r];
;   asm volatile("" : "+v"(ps));
;   ATT_QMM(kb, 1);
;     ...
;   ATT_QRD(kb, 3); asm volatile("s_waitcnt lgkmcnt(4)" ::: "memory"); ATT_SBAR();
;     ...
;   asm volatile("s_waitcnt lgkmcnt(0)" ::: "memory"); ATT_SBAR();
;     ...
;   ATT_QEARLY(kb, 3);
;   { auto rr = __builtin_amdgcn_permlane32_swap(__float_as_uint(ps), __float_as_uint(ps), false, false);
;     ps = __uint_as_float(rr[0]) + __uint_as_float(rr[1]); }
;   l_reg = l_reg * alpha + ps;
;   ATT_PK4(p0, 0, pa0); ATT_PK4(p0, 8, pa1);
;   asm volatile("" : "+v"(l_reg), "+v"(pa0), "+v"(pa1));
;   ATT_QMM(ka, 2);
;   asm volatile("s_waitcnt lgkmcnt(0)" ::: "memory"); ATT_SBAR();
;   ATT_PK4(p1, 0, pa2); ATT_PK4(p1, 8, pa3);
;   asm volatile("" : "+v"(pa2), "+v"(pa3));
;   ATT_QMM(kb, 3);
; template <class CF> __device__ __forceinline__ void pv_sm(f32x16* o, int vb, bf16x8 pa0, bf16x8 pa1, bf16x8 pa2, bf16x8 pa3, f32x16& p0, f32x16& p1, float& m_reg, float& mn, float& alpha) {
;   constexpr float C = CF::SCALE * 1.4426950408889634f;
;   s16x4 f[8];
;   pv_reads<0>(vb, f);
;   float pmax = p0[0];
; #pragma unroll
;   for (int r = 1; r < 16; ++r) pmax = fmaxf(pmax, p0[r]);
;   asm volatile("" : "+v"(pmax));
;   pv_mfma4(o[0], f, pa0, pa1, pa2, pa3);
;   pv_reads<1>(vb, f);
; #pragma unroll
.LBB0_803:
	s_waitcnt lgkmcnt(3)
	v_mfma_f32_32x32x16_bf16 v[112:127], v[206:209], v[156:159], 0
	v_exp_f32_e32 v80, v80
	v_exp_f32_e32 v81, v81
	v_exp_f32_e32 v82, v82
	v_exp_f32_e32 v83, v83
	v_exp_f32_e32 v84, v84
	v_exp_f32_e32 v85, v85
	v_exp_f32_e32 v86, v86
	s_waitcnt lgkmcnt(2)
	v_mfma_f32_32x32x16_bf16 v[96:111], v[210:213], v[156:159], 0
	v_exp_f32_e32 v87, v87
	v_exp_f32_e32 v88, v88
	v_exp_f32_e32 v89, v89
	v_exp_f32_e32 v90, v90
	v_exp_f32_e32 v91, v91
	v_exp_f32_e32 v92, v92
	v_exp_f32_e32 v93, v93
	s_waitcnt lgkmcnt(1)
	v_mfma_f32_32x32x16_bf16 v[112:127], v[218:221], v[152:155], v[112:127]
	ds_read_b128 v[176:179], v231 offset:49152
	ds_read_b128 v[184:187], v231 offset:57344
	ds_read_b128 v[188:191], v232 offset:49152
	ds_read_b128 v[192:195], v232 offset:57344
	v_exp_f32_e32 v94, v94
	v_exp_f32_e32 v95, v95
	s_waitcnt lgkmcnt(4)
	v_mfma_f32_32x32x16_bf16 v[96:111], v[250:253], v[152:155], v[96:111]
	v_add_f32_e32 v196, v65, v64
	v_add_f32_e32 v196, v66, v196
	v_add_f32_e32 v196, v67, v196
	v_add_f32_e32 v196, v68, v196
	v_add_f32_e32 v196, v69, v196
	v_add_f32_e32 v196, v70, v196
	v_add_f32_e32 v196, v71, v196
	v_add_f32_e32 v196, v72, v196
	v_add_f32_e32 v196, v73, v196
	v_add_f32_e32 v196, v74, v196
	v_add_f32_e32 v196, v75, v196
	s_waitcnt lgkmcnt(3)
	v_mfma_f32_32x32x16_bf16 v[112:127], v[176:179], v[148:151], v[112:127]
	v_add_f32_e32 v176, v76, v196
	v_add_f32_e32 v176, v77, v176
	v_add_f32_e32 v176, v78, v176
	v_add_f32_e32 v176, v79, v176
	v_add_f32_e32 v176, v176, v80
	v_add_f32_e32 v176, v81, v176
	v_add_f32_e32 v176, v82, v176
	s_waitcnt lgkmcnt(2)
	v_mfma_f32_32x32x16_bf16 v[96:111], v[184:187], v[148:151], v[96:111]
	v_add_f32_e32 v176, v83, v176
	v_add_f32_e32 v176, v84, v176
	v_add_f32_e32 v176, v85, v176
	v_add_f32_e32 v176, v86, v176
	v_add_f32_e32 v176, v87, v176
	v_add_f32_e32 v176, v88, v176
	v_add_f32_e32 v176, v89, v176
	v_add_f32_e32 v176, v90, v176
	s_waitcnt lgkmcnt(1)
	v_mfma_f32_32x32x16_bf16 v[112:127], v[188:191], v[144:147], v[112:127]
	v_add_f32_e32 v176, v91, v176
	ds_read_b128 v[180:183], v233 offset:49152
	ds_read_b128 v[200:203], v233 offset:57344
	ds_read_b128 v[242:245], v234 offset:49152
	ds_read_b128 v[246:249], v234 offset:57344
	v_add_f32_e32 v176, v92, v176
	v_add_f32_e32 v176, v93, v176
	v_add_f32_e32 v176, v94, v176
	v_add_f32_e32 v196, v95, v176
	s_waitcnt lgkmcnt(4)
	v_mfma_f32_32x32x16_bf16 v[96:111], v[192:195], v[144:147], v[96:111]
	s_waitcnt lgkmcnt(3)
	v_mfma_f32_32x32x16_bf16 v[112:127], v[180:183], v[140:143], v[112:127]
	ds_read_b128 v[176:179], v230 offset:49152
	ds_read_b128 v[184:187], v230 offset:57344
	ds_read_b128 v[188:191], v235 offset:49152
	ds_read_b128 v[250:253], v235 offset:57344
	v_mov_b32_e32 v192, v196
	s_nop 1
	v_permlane32_swap_b32_e32 v196, v192
	v_add_f32_e32 v241, v196, v192
	v_cvt_pk_bf16_f32 v196, v64, v65
	v_cvt_pk_bf16_f32 v197, v66, v67
	s_waitcnt lgkmcnt(6)
	v_mfma_f32_32x32x16_bf16 v[96:111], v[200:203], v[140:143], v[96:111]
	v_cvt_pk_bf16_f32 v198, v68, v69
	v_cvt_pk_bf16_f32 v199, v70, v71
	v_cvt_pk_bf16_f32 v192, v72, v73
	v_cvt_pk_bf16_f32 v193, v74, v75
	v_cvt_pk_bf16_f32 v194, v76, v77
	v_cvt_pk_bf16_f32 v195, v78, v79
	v_fmac_f32_e32 v241, v239, v240
	ds_read_b64_tr_b16 v[64:65], v224 offset:0
	ds_read_b64_tr_b16 v[66:67], v224 offset:0x800
	ds_read_b64_tr_b16 v[68:69], v224 offset:0x1000
	ds_read_b64_tr_b16 v[70:71], v224 offset:0x1800
	s_waitcnt lgkmcnt(9)
	v_mfma_f32_32x32x16_bf16 v[112:127], v[242:245], v[136:139], v[112:127]
	v_permlane32_swap_b32_e32 v196, v198
	v_permlane32_swap_b32_e32 v197, v199
	v_permlane32_swap_b32_e32 v192, v194
	v_permlane32_swap_b32_e32 v193, v195
	ds_read_b64_tr_b16 v[72:73], v224 offset:0x2000
	ds_read_b64_tr_b16 v[74:75], v224 offset:0x2800
	ds_read_b64_tr_b16 v[76:77], v224 offset:0x3000
	ds_read_b64_tr_b16 v[78:79], v224 offset:0x3800
	s_waitcnt lgkmcnt(12)
	v_mfma_f32_32x32x16_bf16 v[96:111], v[246:249], v[136:139], v[96:111]
	s_waitcnt lgkmcnt(11)
	v_mfma_f32_32x32x16_bf16 v[112:127], v[176:179], v[132:135], v[112:127]
	v_cvt_pk_bf16_f32 v200, v80, v81
	v_cvt_pk_bf16_f32 v201, v82, v83
	v_cvt_pk_bf16_f32 v202, v84, v85
	v_cvt_pk_bf16_f32 v203, v86, v87
	v_cvt_pk_bf16_f32 v80, v88, v89
	v_cvt_pk_bf16_f32 v81, v90, v91
	v_cvt_pk_bf16_f32 v82, v92, v93
	s_waitcnt lgkmcnt(10)
	v_mfma_f32_32x32x16_bf16 v[96:111], v[184:187], v[132:135], v[96:111]
	v_cvt_pk_bf16_f32 v83, v94, v95
	v_permlane32_swap_b32_e32 v200, v202
	v_permlane32_swap_b32_e32 v201, v203
	v_permlane32_swap_b32_e32 v80, v82
	s_waitcnt lgkmcnt(9)
	v_mfma_f32_32x32x16_bf16 v[112:127], v[188:191], v[128:131], v[112:127]
	v_permlane32_swap_b32_e32 v81, v83
	s_waitcnt lgkmcnt(8)
	v_mfma_f32_32x32x16_bf16 v[96:111], v[250:253], v[128:131], v[96:111]
	s_waitcnt vmcnt(0)
	s_mov_b32 s11, 0xfff70000
	v_add_co_u32_e32 v84, vcc, s11, v216
	s_mov_b32 s11, 0xfffa0000
	s_nop 0
	v_addc_co_u32_e32 v85, vcc, -1, v217, vcc
	v_add_co_u32_e32 v86, vcc, s11, v216
	s_nop 1
	v_addc_co_u32_e32 v87, vcc, -1, v217, vcc
	global_load_dwordx4 v[176:179], v[84:85], off
	global_load_dwordx4 v[180:183], v[84:85], off offset:-1024
	global_load_dwordx4 v[188:191], v[86:87], off
	global_load_dwordx4 v[184:187], v[86:87], off offset:-1024
	s_waitcnt lgkmcnt(6)
	v_mfma_f32_32x32x16_bf16 v[0:15], v[196:199], v[64:67], v[0:15]
	ds_write_b128 v228, v[168:171] offset:32768
	v_max_f32_e32 v84, v112, v113
	v_max3_f32 v84, v84, v114, v115
	v_max3_f32 v84, v84, v116, v117
	v_max3_f32 v84, v84, v118, v119
	v_max3_f32 v84, v84, v120, v121
	s_waitcnt lgkmcnt(5)
; #define PV_SM(o, vb, a0, a1, a2, a3, q0, q1, m, mn, al) do { if constexpr ((CF::ND0 == 8 || ATT_B_PV) && !MASK) pv_sm<CF>(o, vb, a0, a1, a2, a3, q0, q1, m, mn, al); \
;     else { pv_d0(o, vb, a0, a1, a2, a3); partialSM<CF>(q0, q1, m, mn, al); } } while (0)
; #define PV_SM(o, vb, a0, a1, a2, a3, q0, q1, m, mn, al) do { pv_d0(o, vb, a0, a1, a2, a3); partialSM<CF>(q0, q1, m, mn, al); } while (0)
; #define ATT_SYNC() __syncthreads()
; #define ATT_SWAIT() do { if constexpr (SDEPTH == 2) { if constexpr (ND0 == 12) asm volatile("s_waitcnt vmcnt(5)" ::: "memory"); else asm volatile("s_waitcnt vmcnt(4)" ::: "memory"); } else asm volatile("s_waitcnt vmcnt(0)" ::: "memory"); } while (0)
; template <class CF> __device__ __forceinline__ void pv_sm(f32x16* o, int vb, bf16x8 pa0, bf16x8 pa1, bf16x8 pa2, bf16x8 pa3, f32x16& p0, f32x16& p1, float& m_reg, float& mn, float& alpha) {
;   constexpr float C = CF::SCALE * 1.4426950408889634f;
;   s16x4 f[8];
;   pv_reads<0>(vb, f);
;   float pmax = p0[0];
; #pragma unroll
;   for (int r = 1; r < 16; ++r) pmax = fmaxf(pmax, p0[r]);
;   asm volatile("" : "+v"(pmax));
;   pv_mfma4(o[0], f, pa0, pa1, pa2, pa3);
;   pv_reads<1>(vb, f);
; #pragma unroll
;   for (int r = 0; r < 16; ++r) pmax = fmaxf(pmax, p1[r]);
;   { auto rr = __builtin_amdgcn_permlane32_swap(__float_as_uint(pmax), __float_as_uint(pmax), false, false);
;     pmax = fmaxf(__uint_as_float(rr[0]), __uint_as_float(rr[1])); }
;   asm volatile("" : "+v"(pmax));
;   pv_mfma4(o[1], f, pa0, pa1, pa2, pa3);
;   pv_reads<2>(vb, f);
;   if (__builtin_expect(__all(pmax - m_reg <= THR / CF::SCALE), 1)) { mn = m_reg; alpha = 1.f; }
;   else { mn = fmaxf(m_reg, pmax); alpha = __builtin_amdgcn_exp2f((m_reg - mn) * C); m_reg = mn; }
;   const float mnC = -mn * C;
; #pragma unroll
;   for (int r = 0; r < 16; ++r) p0[r] = fmaf(p0[r], C, mnC);
; #pragma unroll
;   for (int r = 0; r < 16; ++r) p1[r] = fmaf(p1[r], C, mnC);
;   asm volatile("" : "+v"(p0), "+v"(p1));
;   pv_mfma4(o[2], f, pa0, pa1, pa2, pa3);
;   pv_reads<3>(vb, f);
; #pragma unroll
;   for (int r = 0; r < 16; ++r) p0[r] = __builtin_amdgcn_exp2f(p0[r]);
;   asm volatile("" : "+v"(p0));
;   pv_mfma4(o[3], f, pa0, pa1, pa2, pa3);
; }
;     ...
;     PV_SM(o, vb0, pa0, pa1, pa2, pa3, pB0, pB1, m_reg, mnB, alB);
;     ATT_SYNC(); ATT_SWAIT(); ATT_SWRITE(0, SE);
;     ATT_RESC(alB); ATT_SYNC();
	v_mfma_f32_32x32x16_bf16 v[0:15], v[192:195], v[68:71], v[0:15]
	ds_write_b128 v228, v[172:175] offset:40960
	v_max3_f32 v84, v84, v122, v123
	v_max3_f32 v84, v84, v124, v125
	v_max3_f32 v84, v84, v126, v127
	ds_read_b64_tr_b16 v[64:65], v224 offset:0x200
	ds_read_b64_tr_b16 v[66:67], v224 offset:0xa00
	ds_read_b64_tr_b16 v[68:69], v224 offset:0x1200
	s_waitcnt lgkmcnt(7)
	v_mfma_f32_32x32x16_bf16 v[0:15], v[200:203], v[72:75], v[0:15]
	ds_read_b64_tr_b16 v[70:71], v224 offset:0x1a00
	ds_read_b64_tr_b16 v[72:73], v224 offset:0x2200
	ds_read_b64_tr_b16 v[74:75], v224 offset:0x2a00
	s_waitcnt lgkmcnt(8)
	v_mfma_f32_32x32x16_bf16 v[0:15], v[80:83], v[76:79], v[0:15]
	ds_read_b64_tr_b16 v[76:77], v224 offset:0x3200
	ds_read_b64_tr_b16 v[78:79], v224 offset:0x3a00
	s_waitcnt lgkmcnt(6)
	v_mfma_f32_32x32x16_bf16 v[48:63], v[196:199], v[64:67], v[48:63]
	v_max3_f32 v84, v84, v96, v97
	v_max3_f32 v84, v84, v98, v99
	v_max3_f32 v84, v84, v100, v101
	v_max3_f32 v84, v84, v102, v103
	v_max3_f32 v84, v84, v104, v105
	v_max3_f32 v84, v84, v106, v107
	v_max3_f32 v84, v84, v108, v109
	s_waitcnt lgkmcnt(4)
	v_mfma_f32_32x32x16_bf16 v[48:63], v[192:195], v[68:71], v[48:63]
	v_max3_f32 v84, v84, v110, v111
	v_mov_b32_e32 v85, v84
	s_nop 1
	v_permlane32_swap_b32_e32 v84, v85
	v_max_f32_e32 v92, v84, v85
	s_waitcnt lgkmcnt(2)
	v_mfma_f32_32x32x16_bf16 v[48:63], v[200:203], v[72:75], v[48:63]
	ds_read_b64_tr_b16 v[64:65], v224 offset:0x400
	ds_read_b64_tr_b16 v[66:67], v224 offset:0xc00
	ds_read_b64_tr_b16 v[68:69], v224 offset:0x1400
	ds_read_b64_tr_b16 v[70:71], v224 offset:0x1c00
	ds_read_b64_tr_b16 v[84:85], v224 offset:0x2400
	ds_read_b64_tr_b16 v[86:87], v224 offset:0x2c00
	s_waitcnt lgkmcnt(6)
	v_mfma_f32_32x32x16_bf16 v[48:63], v[80:83], v[76:79], v[48:63]
	ds_read_b64_tr_b16 v[88:89], v224 offset:0x3400
	ds_read_b64_tr_b16 v[90:91], v224 offset:0x3c00
	ds_read_b64_tr_b16 v[206:207], v224 offset:0x600
	ds_read_b64_tr_b16 v[208:209], v224 offset:0xe00
	ds_read_b64_tr_b16 v[210:211], v224 offset:0x1600
	ds_read_b64_tr_b16 v[212:213], v224 offset:0x1e00
	s_waitcnt lgkmcnt(10)
	v_mfma_f32_32x32x16_bf16 v[32:47], v[196:199], v[64:67], v[32:47]
	v_sub_f32_e32 v72, v92, v238
	v_cmp_ge_f32_e32 vcc, s66, v72
	v_max_f32_e32 v72, v238, v92
	v_sub_f32_e32 v73, v238, v72
	v_mul_f32_e32 v73, 0x3e0293ee, v73
	ds_read_b64_tr_b16 v[218:219], v224 offset:0x2600
	ds_read_b64_tr_b16 v[220:221], v224 offset:0x2e00
	ds_read_b64_tr_b16 v[246:247], v224 offset:0x3600
	ds_read_b64_tr_b16 v[248:249], v224 offset:0x3e00
	s_waitcnt lgkmcnt(12)
	v_mfma_f32_32x32x16_bf16 v[32:47], v[192:195], v[68:71], v[32:47]
	s_cmp_eq_u64 vcc, exec
	v_exp_f32_e32 v73, v73
	s_cselect_b64 vcc, -1, 0
	v_cndmask_b32_e32 v238, v72, v238, vcc
	v_mul_f32_e32 v92, 0xbe0293ee, v238
	v_cndmask_b32_e64 v239, v73, 1.0, vcc
	v_pk_fma_f32 v[78:79], v[126:127], s[74:75], v[92:93] op_sel_hi:[1,0,0]
	s_waitcnt lgkmcnt(10)
	v_mfma_f32_32x32x16_bf16 v[32:47], v[200:203], v[84:87], v[32:47]
	v_fma_f32 v76, v124, s74, v92
	v_fma_f32 v77, v125, s74, v92
	v_fma_f32 v74, v122, s74, v92
	v_fma_f32 v75, v123, s74, v92
	v_fma_f32 v72, v120, s74, v92
	v_fma_f32 v73, v121, s74, v92
	v_pk_fma_f32 v[70:71], v[118:119], s[74:75], v[92:93] op_sel_hi:[1,0,0]
	v_pk_fma_f32 v[68:69], v[116:117], s[74:75], v[92:93] op_sel_hi:[1,0,0]
	v_pk_fma_f32 v[66:67], v[114:115], s[74:75], v[92:93] op_sel_hi:[1,0,0]
	v_pk_fma_f32 v[64:65], v[112:113], s[74:75], v[92:93] op_sel_hi:[1,0,0]
	v_pk_fma_f32 v[126:127], v[110:111], s[74:75], v[92:93] op_sel_hi:[1,0,0]
	v_pk_fma_f32 v[124:125], v[108:109], s[74:75], v[92:93] op_sel_hi:[1,0,0]
	v_pk_fma_f32 v[122:123], v[106:107], s[74:75], v[92:93] op_sel_hi:[1,0,0]
	v_pk_fma_f32 v[120:121], v[104:105], s[74:75], v[92:93] op_sel_hi:[1,0,0]
	v_pk_fma_f32 v[118:119], v[102:103], s[74:75], v[92:93] op_sel_hi:[1,0,0]
	v_pk_fma_f32 v[116:117], v[100:101], s[74:75], v[92:93] op_sel_hi:[1,0,0]
	v_pk_fma_f32 v[114:115], v[98:99], s[74:75], v[92:93] op_sel_hi:[1,0,0]
	v_pk_fma_f32 v[112:113], v[96:97], s[74:75], v[92:93] op_sel_hi:[1,0,0]
	s_waitcnt lgkmcnt(8)
	v_mfma_f32_32x32x16_bf16 v[32:47], v[80:83], v[88:91], v[32:47]
	s_waitcnt lgkmcnt(0)
	s_barrier
	v_mfma_f32_32x32x16_bf16 v[16:31], v[196:199], v[206:209], v[16:31]
	ds_write_b128 v226, v[160:163]
	v_exp_f32_e32 v96, v64
	v_exp_f32_e32 v97, v65
	v_exp_f32_e32 v98, v66
	v_exp_f32_e32 v99, v67
	v_exp_f32_e32 v100, v68
	v_exp_f32_e32 v101, v69
	v_exp_f32_e32 v102, v70
	v_mfma_f32_32x32x16_bf16 v[16:31], v[192:195], v[210:213], v[16:31]
	ds_write_b128 v227, v[164:167]
	ds_read_b128 v[206:209], v229 offset:32768
	ds_read_b128 v[210:213], v229 offset:40960
	v_exp_f32_e32 v103, v71
	v_exp_f32_e32 v104, v72
	v_exp_f32_e32 v105, v73
	v_exp_f32_e32 v106, v74
	v_exp_f32_e32 v107, v75
	v_exp_f32_e32 v108, v76
	v_exp_f32_e32 v109, v77
	v_mfma_f32_32x32x16_bf16 v[16:31], v[200:203], v[218:221], v[16:31]
	ds_read_b128 v[218:221], v236 offset:32768
	ds_read_b128 v[250:253], v236 offset:40960
	v_exp_f32_e32 v110, v78
	v_exp_f32_e32 v111, v79
	v_mfma_f32_32x32x16_bf16 v[16:31], v[80:83], v[246:249], v[16:31]
	v_cmp_gt_f32_e32 vcc, 1.0, v239
	s_cbranch_vccz .LBB0_807
	s_and_saveexec_b64 s[12:13], s[4:5]
	ds_write_b32 v237, v239 offset:128
	s_or_b64 exec, exec, s[12:13]
	s_waitcnt lgkmcnt(0)
	v_add_u32_e32 v76, v223, v204
	ds_read_b128 v[64:67], v76 offset:224
	ds_read_b128 v[68:71], v76 offset:192
	ds_read_b128 v[72:75], v76 offset:160
	ds_read_b128 v[76:79], v76 offset:128
	s_waitcnt lgkmcnt(3)
	v_pk_mul_f32 v[12:13], v[12:13], v[64:65]
	s_waitcnt lgkmcnt(2)
	v_pk_mul_f32 v[8:9], v[8:9], v[68:69]
	s_waitcnt lgkmcnt(1)
	v_pk_mul_f32 v[4:5], v[4:5], v[72:73]
	v_pk_mul_f32 v[14:15], v[14:15], v[66:67]
	v_pk_mul_f32 v[10:11], v[10:11], v[70:71]
	v_pk_mul_f32 v[6:7], v[6:7], v[74:75]
	s_waitcnt lgkmcnt(0)
	v_pk_mul_f32 v[2:3], v[2:3], v[78:79]
	v_pk_mul_f32 v[0:1], v[0:1], v[76:77]
	v_pk_mul_f32 v[60:61], v[60:61], v[64:65]
	v_pk_mul_f32 v[56:57], v[56:57], v[68:69]
	v_pk_mul_f32 v[52:53], v[52:53], v[72:73]
	v_pk_mul_f32 v[62:63], v[62:63], v[66:67]
	v_pk_mul_f32 v[58:59], v[58:59], v[70:71]
	v_pk_mul_f32 v[54:55], v[54:55], v[74:75]
	v_pk_mul_f32 v[50:51], v[50:51], v[78:79]
	v_pk_mul_f32 v[48:49], v[48:49], v[76:77]
	v_pk_mul_f32 v[44:45], v[44:45], v[64:65]
	v_pk_mul_f32 v[40:41], v[40:41], v[68:69]
	v_pk_mul_f32 v[36:37], v[36:37], v[72:73]
	v_pk_mul_f32 v[46:47], v[46:47], v[66:67]
	v_pk_mul_f32 v[42:43], v[42:43], v[70:71]
	v_pk_mul_f32 v[38:39], v[38:39], v[74:75]
	v_pk_mul_f32 v[34:35], v[34:35], v[78:79]
	v_pk_mul_f32 v[32:33], v[32:33], v[76:77]
	v_pk_mul_f32 v[28:29], v[28:29], v[64:65]
	v_pk_mul_f32 v[24:25], v[24:25], v[68:69]
	v_pk_mul_f32 v[20:21], v[20:21], v[72:73]
	v_pk_mul_f32 v[30:31], v[30:31], v[66:67]
	v_pk_mul_f32 v[26:27], v[26:27], v[70:71]
	v_pk_mul_f32 v[22:23], v[22:23], v[74:75]
	v_pk_mul_f32 v[18:19], v[18:19], v[78:79]
	v_pk_mul_f32 v[16:17], v[16:17], v[76:77]
; template <class CF> __device__ __forceinline__ void qk_sm(f32x16& n0, f32x16& n1, const char* Ks, const bf16x8* qr, int r32, int hi,
;                                                           f32x16& p0, f32x16& p1, float alpha, float& l_reg, bf16x8& pa0, bf16x8& pa1, bf16x8& pa2, bf16x8& pa3) {
;   n0 = f32x16{}; n1 = f32x16{};
;   const char* kr = Ks + r32 * CF::KPITCH; const int sw = (r32 & CF::KSWM) << 4;
;   bf16x8 ka[4], kb[4];
;     ...
;   ATT_QRD(ka, 0); ATT_QRD(kb, 1); asm volatile("s_waitcnt lgkmcnt(4)" ::: "memory"); ATT_SBAR();
;     ...
;   ATT_QRD(ka, 0); asm volatile("s_waitcnt lgkmcnt(0)" ::: "memory"); ATT_SBAR();
;     ...
;   ATT_QEARLY(kb, 1);
; #pragma unroll
;   for (int r = 0; r < 16; ++r) p1[r] = __builtin_amdgcn_exp2f(p1[r]);
;   asm volatile("" : "+v"(p1));
;   ATT_QMM(ka, 0);
;     ...
;   ATT_QRD(ka, 2); asm volatile("s_waitcnt lgkmcnt(4)" ::: "memory"); ATT_SBAR();
;     ...
;   asm volatile("s_waitcnt lgkmcnt(0)" ::: "memory"); ATT_SBAR();
;     ...
;   ATT_QEARLY(ka, 2);
;   float ps = 0;
; #pragma unroll
;   for (int r = 0; r < 16; ++r) ps += p0[r];
; #pragma unroll
;   for (int r = 0; r < 16; ++r) ps += p1[r];
;   asm volatile("" : "+v"(ps));
;   ATT_QMM(kb, 1);
;     ...
;   ATT_QRD(kb, 3); asm volatile("s_waitcnt lgkmcnt(4)" ::: "memory"); ATT_SBAR();
;     ...
;   asm volatile("s_waitcnt lgkmcnt(0)" ::: "memory"); ATT_SBAR();
;     ...
;   ATT_QEARLY(kb, 3);
;   { auto rr = __builtin_amdgcn_permlane32_swap(__float_as_uint(ps), __float_as_uint(ps), false, false);
;     ps = __uint_as_float(rr[0]) + __uint_as_float(rr[1]); }
;   l_reg = l_reg * alpha + ps;
;   ATT_PK4(p0, 0, pa0); ATT_PK4(p0, 8, pa1);
;   asm volatile("" : "+v"(l_reg), "+v"(pa0), "+v"(pa1));
;   ATT_QMM(ka, 2);
;   asm volatile("s_waitcnt lgkmcnt(0)" ::: "memory"); ATT_SBAR();
;   ATT_PK4(p1, 0, pa2); ATT_PK4(p1, 8, pa3);
;   asm volatile("" : "+v"(pa2), "+v"(pa3));
;   ATT_QMM(kb, 3);
;     ...
;     ATT_SBAR(); if constexpr (QKSPLIT) qk_sm<CF>(pA0, pA1, K_lds, qr, r32, hi, pB0, pB1, alB, l_reg, pa0, pa1, pa2, pa3);
;     else if constexpr (QK1) qk_sm1<CF>(pA0, pA1, K_lds, qr, qx, r32, hi, pB0, pB1, alB, l_reg, pa0, pa1, pa2, pa3);
;     else { qkt<CF>(pA0, pA1, K_lds, qr, qx, r32, hi); if constexpr (MASK) bandmask(pA0, pA1, (j + 1) * KVBLK, qi, hi);
;     finishSM(pB0, pB1, alB, l_reg, pa0, pa1, pa2, pa3); } ATT_SBAR();
;     if (SDEPTH == 1 || j + 3 < NT) ATT_SLOAD(SE, (j + 1 + SDEPTH) * KVBLK); ATT_SBAR();
.LBB0_807:
	s_waitcnt lgkmcnt(3)
	v_mfma_f32_32x32x16_bf16 v[80:95], v[206:209], v[156:159], 0
	v_exp_f32_e32 v112, v112
	v_exp_f32_e32 v113, v113
	v_exp_f32_e32 v114, v114
	v_exp_f32_e32 v115, v115
	v_exp_f32_e32 v116, v116
	v_exp_f32_e32 v117, v117
	v_exp_f32_e32 v118, v118
	s_waitcnt lgkmcnt(2)
	v_mfma_f32_32x32x16_bf16 v[64:79], v[210:213], v[156:159], 0
	v_exp_f32_e32 v119, v119
	v_exp_f32_e32 v120, v120
	v_exp_f32_e32 v121, v121
	v_exp_f32_e32 v122, v122
	v_exp_f32_e32 v123, v123
	v_exp_f32_e32 v124, v124
	v_exp_f32_e32 v125, v125
	s_waitcnt lgkmcnt(1)
	v_mfma_f32_32x32x16_bf16 v[80:95], v[218:221], v[152:155], v[80:95]
	ds_read_b128 v[192:195], v231 offset:32768
	ds_read_b128 v[200:203], v231 offset:40960
	ds_read_b128 v[242:245], v232 offset:32768
	ds_read_b128 v[246:249], v232 offset:40960
	v_exp_f32_e32 v126, v126
	v_exp_f32_e32 v127, v127
	s_waitcnt lgkmcnt(4)
	v_mfma_f32_32x32x16_bf16 v[64:79], v[250:253], v[152:155], v[64:79]
	v_add_f32_e32 v218, v97, v96
	v_add_f32_e32 v218, v98, v218
	v_add_f32_e32 v218, v99, v218
	v_add_f32_e32 v218, v100, v218
	v_add_f32_e32 v218, v101, v218
	v_add_f32_e32 v218, v102, v218
	v_add_f32_e32 v218, v103, v218
	v_add_f32_e32 v218, v104, v218
	v_add_f32_e32 v218, v105, v218
	v_add_f32_e32 v218, v106, v218
	v_add_f32_e32 v218, v107, v218
	s_waitcnt lgkmcnt(3)
	v_mfma_f32_32x32x16_bf16 v[80:95], v[192:195], v[148:151], v[80:95]
	v_add_f32_e32 v192, v108, v218
	v_add_f32_e32 v192, v109, v192
	v_add_f32_e32 v192, v110, v192
	v_add_f32_e32 v192, v111, v192
	v_add_f32_e32 v192, v192, v112
	v_add_f32_e32 v192, v113, v192
	v_add_f32_e32 v192, v114, v192
	s_waitcnt lgkmcnt(2)
	v_mfma_f32_32x32x16_bf16 v[64:79], v[200:203], v[148:151], v[64:79]
	v_add_f32_e32 v192, v115, v192
	v_add_f32_e32 v192, v116, v192
	v_add_f32_e32 v192, v117, v192
	v_add_f32_e32 v192, v118, v192
	v_add_f32_e32 v192, v119, v192
	v_add_f32_e32 v192, v120, v192
	v_add_f32_e32 v192, v121, v192
	v_add_f32_e32 v192, v122, v192
	s_waitcnt lgkmcnt(1)
	v_mfma_f32_32x32x16_bf16 v[80:95], v[242:245], v[144:147], v[80:95]
	v_add_f32_e32 v192, v123, v192
	ds_read_b128 v[196:199], v233 offset:32768
	ds_read_b128 v[250:253], v233 offset:40960
	ds_read_b128 v[210:213], v234 offset:32768
	ds_read_b128 v[206:209], v234 offset:40960
	v_add_f32_e32 v192, v124, v192
	v_add_f32_e32 v192, v125, v192
	v_add_f32_e32 v192, v126, v192
	v_add_f32_e32 v192, v127, v192
	s_waitcnt lgkmcnt(4)
	v_mfma_f32_32x32x16_bf16 v[64:79], v[246:249], v[144:147], v[64:79]
	s_waitcnt lgkmcnt(3)
	v_mfma_f32_32x32x16_bf16 v[80:95], v[196:199], v[140:143], v[80:95]
	ds_read_b128 v[200:203], v230 offset:32768
	ds_read_b128 v[242:245], v230 offset:40960
	ds_read_b128 v[246:249], v235 offset:32768
	ds_read_b128 v[218:221], v235 offset:40960
	v_mov_b32_e32 v193, v192
	s_nop 1
	v_permlane32_swap_b32_e32 v192, v193
	v_add_f32_e32 v240, v192, v193
	v_cvt_pk_bf16_f32 v196, v96, v97
	v_cvt_pk_bf16_f32 v197, v98, v99
	s_waitcnt lgkmcnt(6)
	v_mfma_f32_32x32x16_bf16 v[64:79], v[250:253], v[140:143], v[64:79]
	v_cvt_pk_bf16_f32 v198, v100, v101
	v_cvt_pk_bf16_f32 v199, v102, v103
	v_cvt_pk_bf16_f32 v192, v104, v105
	v_cvt_pk_bf16_f32 v193, v106, v107
	v_cvt_pk_bf16_f32 v194, v108, v109
	v_cvt_pk_bf16_f32 v195, v110, v111
	v_fmac_f32_e32 v240, v241, v239
	ds_read_b64_tr_b16 v[96:97], v225 offset:0
	ds_read_b64_tr_b16 v[98:99], v225 offset:0x800
	ds_read_b64_tr_b16 v[100:101], v225 offset:0x1000
	ds_read_b64_tr_b16 v[102:103], v225 offset:0x1800
	s_waitcnt lgkmcnt(9)
	v_mfma_f32_32x32x16_bf16 v[80:95], v[210:213], v[136:139], v[80:95]
	v_permlane32_swap_b32_e32 v196, v198
	v_permlane32_swap_b32_e32 v197, v199
	v_permlane32_swap_b32_e32 v192, v194
	v_permlane32_swap_b32_e32 v193, v195
	ds_read_b64_tr_b16 v[104:105], v225 offset:0x2000
	ds_read_b64_tr_b16 v[106:107], v225 offset:0x2800
	ds_read_b64_tr_b16 v[108:109], v225 offset:0x3000
	ds_read_b64_tr_b16 v[110:111], v225 offset:0x3800
	s_waitcnt lgkmcnt(12)
	v_mfma_f32_32x32x16_bf16 v[64:79], v[206:209], v[136:139], v[64:79]
	s_waitcnt lgkmcnt(11)
	v_mfma_f32_32x32x16_bf16 v[80:95], v[200:203], v[132:135], v[80:95]
	v_cvt_pk_bf16_f32 v200, v112, v113
	v_cvt_pk_bf16_f32 v201, v114, v115
	v_cvt_pk_bf16_f32 v202, v116, v117
	v_cvt_pk_bf16_f32 v203, v118, v119
	v_cvt_pk_bf16_f32 v112, v120, v121
	v_cvt_pk_bf16_f32 v113, v122, v123
	v_cvt_pk_bf16_f32 v114, v124, v125
	s_waitcnt lgkmcnt(10)
	v_mfma_f32_32x32x16_bf16 v[64:79], v[242:245], v[132:135], v[64:79]
	v_cvt_pk_bf16_f32 v115, v126, v127
	v_permlane32_swap_b32_e32 v200, v202
	v_permlane32_swap_b32_e32 v201, v203
	v_permlane32_swap_b32_e32 v112, v114
	s_waitcnt lgkmcnt(9)
	v_mfma_f32_32x32x16_bf16 v[80:95], v[246:249], v[128:131], v[80:95]
	v_permlane32_swap_b32_e32 v113, v115
	s_waitcnt lgkmcnt(8)
	v_mfma_f32_32x32x16_bf16 v[64:79], v[218:221], v[128:131], v[64:79]
	s_waitcnt vmcnt(0)
	s_add_i32 s10, s10, 2
	s_cmp_ge_u32 s10, s0
	s_cselect_b64 s[12:13], -1, 0
	s_and_b64 vcc, exec, s[12:13]
	s_cbranch_vccnz .LBB0_809
	v_add_co_u32_e32 v116, vcc, 0xfffd0000, v216
	s_nop 1
	v_addc_co_u32_e32 v117, vcc, -1, v217, vcc
	global_load_dwordx4 v[160:163], v[116:117], off
	global_load_dwordx4 v[168:171], v[116:117], off offset:-1024
	global_load_dwordx4 v[164:167], v[216:217], off
	global_load_dwordx4 v[172:175], v[216:217], off offset:-1024
; #define PV_SM(o, vb, a0, a1, a2, a3, q0, q1, m, mn, al) do { if constexpr ((CF::ND0 == 8 || ATT_B_PV) && !MASK) pv_sm<CF>(o, vb, a0, a1, a2, a3, q0, q1, m, mn, al); \
;     else { pv_d0(o, vb, a0, a1, a2, a3); partialSM<CF>(q0, q1, m, mn, al); } } while (0)
; #define PV_SM(o, vb, a0, a1, a2, a3, q0, q1, m, mn, al) do { pv_d0(o, vb, a0, a1, a2, a3); partialSM<CF>(q0, q1, m, mn, al); } while (0)
; #define ATT_SYNC() __syncthreads()
; #define ATT_SWAIT() do { if constexpr (SDEPTH == 2) { if constexpr (ND0 == 12) asm volatile("s_waitcnt vmcnt(5)" ::: "memory"); else asm volatile("s_waitcnt vmcnt(4)" ::: "memory"); } else asm volatile("s_waitcnt vmcnt(0)" ::: "memory"); } while (0)
; template <class CF> __device__ __forceinline__ void pv_sm(f32x16* o, int vb, bf16x8 pa0, bf16x8 pa1, bf16x8 pa2, bf16x8 pa3, f32x16& p0, f32x16& p1, float& m_reg, float& mn, float& alpha) {
;   constexpr float C = CF::SCALE * 1.4426950408889634f;
;   s16x4 f[8];
;   pv_reads<0>(vb, f);
;   float pmax = p0[0];
; #pragma unroll
;   for (int r = 1; r < 16; ++r) pmax = fmaxf(pmax, p0[r]);
;   asm volatile("" : "+v"(pmax));
;   pv_mfma4(o[0], f, pa0, pa1, pa2, pa3);
;   pv_reads<1>(vb, f);
; #pragma unroll
;   for (int r = 0; r < 16; ++r) pmax = fmaxf(pmax, p1[r]);
;   { auto rr = __builtin_amdgcn_permlane32_swap(__float_as_uint(pmax), __float_as_uint(pmax), false, false);
;     pmax = fmaxf(__uint_as_float(rr[0]), __uint_as_float(rr[1])); }
;   asm volatile("" : "+v"(pmax));
;   pv_mfma4(o[1], f, pa0, pa1, pa2, pa3);
;   pv_reads<2>(vb, f);
;   if (__builtin_expect(__all(pmax - m_reg <= THR / CF::SCALE), 1)) { mn = m_reg; alpha = 1.f; }
;   else { mn = fmaxf(m_reg, pmax); alpha = __builtin_amdgcn_exp2f((m_reg - mn) * C); m_reg = mn; }
;   const float mnC = -mn * C;
; #pragma unroll
;   for (int r = 0; r < 16; ++r) p0[r] = fmaf(p0[r], C, mnC);
; #pragma unroll
;   for (int r = 0; r < 16; ++r) p1[r] = fmaf(p1[r], C, mnC);
;   asm volatile("" : "+v"(p0), "+v"(p1));
;   pv_mfma4(o[2], f, pa0, pa1, pa2, pa3);
;   pv_reads<3>(vb, f);
; #pragma unroll
;   for (int r = 0; r < 16; ++r) p0[r] = __builtin_amdgcn_exp2f(p0[r]);
;   asm volatile("" : "+v"(p0));
;   pv_mfma4(o[3], f, pa0, pa1, pa2, pa3);
; }
;     ...
;     PV_SM(o, vb0 + SHM_V, pa0, pa1, pa2, pa3, pA0, pA1, m_reg, mnA, alA);
;     ATT_SYNC(); ATT_SWAIT(); ATT_SWRITE(1, SO);
;     ATT_RESC(alA); ATT_SYNC();
.LBB0_809:
	s_waitcnt lgkmcnt(6)
	v_mfma_f32_32x32x16_bf16 v[0:15], v[196:199], v[96:99], v[0:15]
	ds_write_b128 v228, v[180:183] offset:49152
	s_nop 1
	v_max_f32_e32 v116, v80, v81
	v_max3_f32 v116, v116, v82, v83
	v_max3_f32 v116, v116, v84, v85
	v_max3_f32 v116, v116, v86, v87
	v_max3_f32 v116, v116, v88, v89
	s_waitcnt lgkmcnt(5)
	v_mfma_f32_32x32x16_bf16 v[0:15], v[192:195], v[100:103], v[0:15]
	ds_write_b128 v228, v[184:187] offset:57344
	v_max3_f32 v116, v116, v90, v91
	v_max3_f32 v116, v116, v92, v93
	v_max3_f32 v116, v116, v94, v95
	ds_read_b64_tr_b16 v[96:97], v225 offset:0x200
	ds_read_b64_tr_b16 v[98:99], v225 offset:0xa00
	ds_read_b64_tr_b16 v[100:101], v225 offset:0x1200
	s_waitcnt lgkmcnt(7)
	v_mfma_f32_32x32x16_bf16 v[0:15], v[200:203], v[104:107], v[0:15]
	ds_read_b64_tr_b16 v[102:103], v225 offset:0x1a00
	ds_read_b64_tr_b16 v[104:105], v225 offset:0x2200
	ds_read_b64_tr_b16 v[106:107], v225 offset:0x2a00
	s_waitcnt lgkmcnt(8)
	v_mfma_f32_32x32x16_bf16 v[0:15], v[112:115], v[108:111], v[0:15]
	ds_read_b64_tr_b16 v[108:109], v225 offset:0x3200
	ds_read_b64_tr_b16 v[110:111], v225 offset:0x3a00
	s_waitcnt lgkmcnt(6)
	v_mfma_f32_32x32x16_bf16 v[48:63], v[196:199], v[96:99], v[48:63]
	v_max3_f32 v116, v116, v64, v65
	v_max3_f32 v116, v116, v66, v67
	v_max3_f32 v116, v116, v68, v69
	v_max3_f32 v116, v116, v70, v71
	v_max3_f32 v116, v116, v72, v73
	v_max3_f32 v116, v116, v74, v75
	v_max3_f32 v116, v116, v76, v77
	s_waitcnt lgkmcnt(4)
	v_mfma_f32_32x32x16_bf16 v[48:63], v[192:195], v[100:103], v[48:63]
	v_max3_f32 v116, v116, v78, v79
	v_mov_b32_e32 v117, v116
	s_nop 1
	v_permlane32_swap_b32_e32 v116, v117
	v_max_f32_e32 v124, v116, v117
	s_waitcnt lgkmcnt(2)
	v_mfma_f32_32x32x16_bf16 v[48:63], v[200:203], v[104:107], v[48:63]
	ds_read_b64_tr_b16 v[96:97], v225 offset:0x400
	ds_read_b64_tr_b16 v[98:99], v225 offset:0xc00
	ds_read_b64_tr_b16 v[100:101], v225 offset:0x1400
	ds_read_b64_tr_b16 v[102:103], v225 offset:0x1c00
	ds_read_b64_tr_b16 v[116:117], v225 offset:0x2400
	ds_read_b64_tr_b16 v[118:119], v225 offset:0x2c00
	s_waitcnt lgkmcnt(6)
	v_mfma_f32_32x32x16_bf16 v[48:63], v[112:115], v[108:111], v[48:63]
	ds_read_b64_tr_b16 v[120:121], v225 offset:0x3400
	ds_read_b64_tr_b16 v[122:123], v225 offset:0x3c00
	ds_read_b64_tr_b16 v[206:207], v225 offset:0x600
	ds_read_b64_tr_b16 v[208:209], v225 offset:0xe00
	ds_read_b64_tr_b16 v[210:211], v225 offset:0x1600
	ds_read_b64_tr_b16 v[212:213], v225 offset:0x1e00
	s_waitcnt lgkmcnt(10)
	v_mfma_f32_32x32x16_bf16 v[32:47], v[196:199], v[96:99], v[32:47]
	v_sub_f32_e32 v104, v124, v238
	v_cmp_ge_f32_e32 vcc, s66, v104
	v_max_f32_e32 v104, v238, v124
	v_sub_f32_e32 v105, v238, v104
	v_mul_f32_e32 v105, 0x3e0293ee, v105
	ds_read_b64_tr_b16 v[218:219], v225 offset:0x2600
	ds_read_b64_tr_b16 v[220:221], v225 offset:0x2e00
	ds_read_b64_tr_b16 v[246:247], v225 offset:0x3600
	ds_read_b64_tr_b16 v[248:249], v225 offset:0x3e00
	s_waitcnt lgkmcnt(12)
	v_mfma_f32_32x32x16_bf16 v[32:47], v[192:195], v[100:103], v[32:47]
	s_cmp_eq_u64 vcc, exec
	v_exp_f32_e32 v105, v105
	s_cselect_b64 vcc, -1, 0
	v_cndmask_b32_e32 v238, v104, v238, vcc
	v_mul_f32_e32 v124, 0xbe0293ee, v238
	v_cndmask_b32_e64 v239, v105, 1.0, vcc
	v_pk_fma_f32 v[110:111], v[94:95], s[74:75], v[124:125] op_sel_hi:[1,0,0]
	s_waitcnt lgkmcnt(10)
	v_mfma_f32_32x32x16_bf16 v[32:47], v[200:203], v[116:119], v[32:47]
	v_fma_f32 v108, v92, s74, v124
	v_fma_f32 v109, v93, s74, v124
	v_fma_f32 v106, v90, s74, v124
	v_fma_f32 v107, v91, s74, v124
	v_fma_f32 v104, v88, s74, v124
	v_fma_f32 v105, v89, s74, v124
	v_pk_fma_f32 v[102:103], v[86:87], s[74:75], v[124:125] op_sel_hi:[1,0,0]
	v_pk_fma_f32 v[100:101], v[84:85], s[74:75], v[124:125] op_sel_hi:[1,0,0]
	v_pk_fma_f32 v[98:99], v[82:83], s[74:75], v[124:125] op_sel_hi:[1,0,0]
	v_pk_fma_f32 v[96:97], v[80:81], s[74:75], v[124:125] op_sel_hi:[1,0,0]
	v_pk_fma_f32 v[94:95], v[78:79], s[74:75], v[124:125] op_sel_hi:[1,0,0]
	v_pk_fma_f32 v[92:93], v[76:77], s[74:75], v[124:125] op_sel_hi:[1,0,0]
	v_pk_fma_f32 v[90:91], v[74:75], s[74:75], v[124:125] op_sel_hi:[1,0,0]
	v_pk_fma_f32 v[88:89], v[72:73], s[74:75], v[124:125] op_sel_hi:[1,0,0]
	v_pk_fma_f32 v[86:87], v[70:71], s[74:75], v[124:125] op_sel_hi:[1,0,0]
	v_pk_fma_f32 v[84:85], v[68:69], s[74:75], v[124:125] op_sel_hi:[1,0,0]
	v_pk_fma_f32 v[82:83], v[66:67], s[74:75], v[124:125] op_sel_hi:[1,0,0]
	v_pk_fma_f32 v[80:81], v[64:65], s[74:75], v[124:125] op_sel_hi:[1,0,0]
	s_waitcnt lgkmcnt(8)
	v_mfma_f32_32x32x16_bf16 v[32:47], v[112:115], v[120:123], v[32:47]
	s_waitcnt lgkmcnt(0)
	s_barrier
	v_mfma_f32_32x32x16_bf16 v[16:31], v[196:199], v[206:209], v[16:31]
	ds_write_b128 v226, v[176:179] offset:16384
	v_exp_f32_e32 v64, v96
	v_exp_f32_e32 v65, v97
	v_exp_f32_e32 v66, v98
	v_exp_f32_e32 v67, v99
	v_exp_f32_e32 v68, v100
	v_exp_f32_e32 v69, v101
	v_exp_f32_e32 v70, v102
	v_mfma_f32_32x32x16_bf16 v[16:31], v[192:195], v[210:213], v[16:31]
	ds_write_b128 v227, v[188:191] offset:16384
	ds_read_b128 v[206:209], v229 offset:49152
	ds_read_b128 v[210:213], v229 offset:57344
	v_exp_f32_e32 v71, v103
	v_exp_f32_e32 v72, v104
	v_exp_f32_e32 v73, v105
	v_exp_f32_e32 v74, v106
	v_exp_f32_e32 v75, v107
	v_exp_f32_e32 v76, v108
	v_exp_f32_e32 v77, v109
	v_mfma_f32_32x32x16_bf16 v[16:31], v[200:203], v[218:221], v[16:31]
	ds_read_b128 v[218:221], v236 offset:49152
	ds_read_b128 v[250:253], v236 offset:57344
	v_exp_f32_e32 v78, v110
	v_exp_f32_e32 v79, v111
	v_mfma_f32_32x32x16_bf16 v[16:31], v[112:115], v[246:249], v[16:31]
	v_cmp_gt_f32_e32 vcc, 1.0, v239
	s_cbranch_vccz .LBB0_802
	s_and_saveexec_b64 s[14:15], s[4:5]
	s_cbranch_execz .LBB0_801
	ds_write_b32 v237, v239 offset:128
	s_branch .LBB0_801

; #define ATT_SBAR() __builtin_amdgcn_sched_barrier(0)
; template <class CF> __device__ __forceinline__ void qk_sm1(f32x16& n0, f32x16& n1, const char* Ks, const bf16x8* qr, const char* qx, int r32, int hi, ...
;   static_assert(CF::ND0 == 12, "qk_sm1: 12 d0 steps");
;   n0 = f32x16{}; n1 = f32x16{};
;   const char* kr = Ks + r32 * CF::KPITCH; const int sw = (r32 & CF::KSWM) << 4;
;   bf16x8 kf[2][2], qf[2];
;     ...
;   ATT_QRD(0, 0); asm volatile("s_waitcnt lgkmcnt(0)" ::: "memory"); ATT_SBAR();
;   float ps = 0;
; #pragma unroll
;   for (int g = 0; g < 12; ++g) {
;     if (g + 1 < 12) ATT_QRD((g + 1) & 1, g + 1);
;     if (g < 2) {
; #pragma unroll
;       for (int r = 0; r < 8; ++r) p1[8 * g + r] = __builtin_amdgcn_exp2f(p1[8 * g + r]);
;       if (g == 1) asm volatile("" : "+v"(p1)); }
;     else if (g < 6) {
; #pragma unroll
;       for (int r = 0; r < 8; ++r) ps += (g < 4 ? p0[8 * (g - 2) + r] : p1[8 * (g - 4) + r]);
;       asm volatile("" : "+v"(ps)); }
;     else if (g == 6) {
;       { auto rr = __builtin_amdgcn_permlane32_swap(__float_as_uint(ps), __float_as_uint(ps), false, false);
;         ps = __uint_as_float(rr[0]) + __uint_as_float(rr[1]); }
;       l_reg = l_reg * alpha + ps;
;       ATT_PK4(p0, 0, pa0);
;       asm volatile("" : "+v"(l_reg), "+v"(pa0)); }
;     else if (g == 7) { ATT_PK4(p0, 8, pa1); asm volatile("" : "+v"(pa1)); }
;     else if (g == 8) { ATT_PK4(p1, 0, pa2); asm volatile("" : "+v"(pa2)); }
;     else if (g == 9) { ATT_PK4(p1, 8, pa3); asm volatile("" : "+v"(pa3)); }
;     ATT_QMM(g & 1, g);
;     if (g + 1 < 12) { asm volatile("s_waitcnt lgkmcnt(0)" ::: "memory"); ATT_SBAR(); }
;   }
;     ...
;   for (int j = 1; j + 1 < NT; j += 2) {
;     ATT_SBAR(); if constexpr (QKSPLIT) qk_sm<CF>(pB0, pB1, K_lds + SHM_K, qr, r32, hi, pA0, pA1, alA, l_reg, pa0, pa1, pa2, pa3);
;     else if constexpr (QK1) qk_sm1<CF>(pB0, pB1, K_lds + SHM_K, qr, qx, r32, hi, pA0, pA1, alA, l_reg, pa0, pa1, pa2, pa3);
;     else { qkt<CF>(pB0, pB1, K_lds + SHM_K, qr, qx, r32, hi); if constexpr (MASK) bandmask(pB0, pB1, j * KVBLK, qi, hi);
;     finishSM(pA0, pA1, alA, l_reg, pa0, pa1, pa2, pa3); } ATT_SBAR();
;     ATT_SLOAD(SO, (j + SDEPTH) * KVBLK); ATT_SBAR();
.LBB0_1724:
	s_add_i32 s22, s22, 2
	v_lshl_add_u64 v[174:175], v[174:175], 0, s[86:87]
	v_lshl_add_u64 v[176:177], v[176:177], 0, s[86:87]
	s_cmp_ge_u32 s22, s21
	v_lshl_add_u64 v[178:179], v[178:179], 0, s[82:83]
	s_cbranch_scc1 .LBB0_1732
.LBB0_1725:
	v_add_u32_e32 v237, v200, v236
	v_add_u32_e32 v238, v235, v236
	ds_read_b128 v[96:99], v237 offset:57344
	ds_read_b128 v[100:103], v238 offset:12288
	s_waitcnt lgkmcnt(1)
	v_mfma_f32_32x32x16_bf16 v[112:127], v[96:99], v[148:151], 0
	v_add_u32_e32 v239, v235, v216
	ds_read_b128 v[152:155], v215 offset:57344
	ds_read_b128 v[156:159], v239 offset:12288
	v_exp_f32_e32 v80, v80
	v_exp_f32_e32 v81, v81
	v_exp_f32_e32 v82, v82
	v_exp_f32_e32 v83, v83
	s_waitcnt lgkmcnt(2)
	v_mfma_f32_32x32x16_bf16 v[96:111], v[100:103], v[148:151], 0
	v_exp_f32_e32 v84, v84
	v_exp_f32_e32 v85, v85
	v_exp_f32_e32 v86, v86
	v_exp_f32_e32 v87, v87
	s_waitcnt lgkmcnt(1)
	v_mfma_f32_32x32x16_bf16 v[112:127], v[152:155], v[144:147], v[112:127]
	v_add_u32_e32 v240, v235, v217
	ds_read_b128 v[152:155], v203 offset:57344
	ds_read_b128 v[160:163], v240 offset:12288
	v_exp_f32_e32 v88, v88
	v_exp_f32_e32 v89, v89
	v_exp_f32_e32 v90, v90
	v_exp_f32_e32 v91, v91
	v_exp_f32_e32 v92, v92
	s_waitcnt lgkmcnt(2)
	v_mfma_f32_32x32x16_bf16 v[96:111], v[156:159], v[144:147], v[96:111]
	v_exp_f32_e32 v93, v93
	v_exp_f32_e32 v94, v94
	v_exp_f32_e32 v95, v95
	v_add_f32_e32 v168, v65, v64
	v_add_f32_e32 v168, v66, v168
	s_waitcnt lgkmcnt(1)
	v_mfma_f32_32x32x16_bf16 v[112:127], v[152:155], v[140:143], v[112:127]
	v_add_f32_e32 v152, v67, v168
	v_add_f32_e32 v152, v68, v152
	v_add_f32_e32 v152, v69, v152
	v_add_u32_e32 v241, v235, v223
	ds_read_b128 v[156:159], v214 offset:57344
	ds_read_b128 v[164:167], v241 offset:12288
	v_add_f32_e32 v152, v70, v152
	v_add_f32_e32 v168, v71, v152
	s_waitcnt lgkmcnt(2)
	v_mfma_f32_32x32x16_bf16 v[96:111], v[160:163], v[140:143], v[96:111]
	s_nop 0
	v_add_f32_e32 v168, v72, v168
	v_add_f32_e32 v168, v73, v168
	v_add_f32_e32 v168, v74, v168
	s_waitcnt lgkmcnt(1)
	v_mfma_f32_32x32x16_bf16 v[112:127], v[156:159], v[136:139], v[112:127]
	v_add_f32_e32 v156, v75, v168
	v_add_f32_e32 v156, v76, v156
	v_add_f32_e32 v156, v77, v156
	v_add_u32_e32 v242, v235, v225
	ds_read_b128 v[152:155], v202 offset:57344
	ds_read_b128 v[160:163], v242 offset:12288
	v_add_f32_e32 v156, v78, v156
	v_add_f32_e32 v168, v79, v156
	s_waitcnt lgkmcnt(2)
	v_mfma_f32_32x32x16_bf16 v[96:111], v[164:167], v[136:139], v[96:111]
	s_nop 0
	v_add_f32_e32 v168, v80, v168
	v_add_f32_e32 v168, v81, v168
	v_add_f32_e32 v168, v82, v168
	s_waitcnt lgkmcnt(1)
	v_mfma_f32_32x32x16_bf16 v[112:127], v[152:155], v[132:135], v[112:127]
	v_add_f32_e32 v152, v83, v168
	v_add_f32_e32 v152, v84, v152
	v_add_f32_e32 v152, v85, v152
	v_add_u32_e32 v243, v235, v226
	ds_read_b128 v[156:159], v201 offset:57344
	ds_read_b128 v[164:167], v243 offset:12288
	v_add_f32_e32 v152, v86, v152
	v_add_f32_e32 v152, v87, v152
	s_waitcnt lgkmcnt(2)
	v_mfma_f32_32x32x16_bf16 v[96:111], v[160:163], v[132:135], v[96:111]
	s_nop 0
	v_add_f32_e32 v152, v88, v152
	v_add_f32_e32 v152, v89, v152
	v_add_f32_e32 v152, v90, v152
	s_waitcnt lgkmcnt(1)
	v_mfma_f32_32x32x16_bf16 v[112:127], v[156:159], v[128:131], v[112:127]
	v_add_f32_e32 v152, v91, v152
	v_add_u32_e32 v244, v235, v227
	v_add_f32_e32 v152, v92, v152
	ds_read_b128 v[160:163], v244 offset:12288
	ds_read_b128 v[168:171], v198 offset:57344
	ds_read_b128 v[182:185], v188
	v_add_f32_e32 v152, v93, v152
	v_add_f32_e32 v152, v94, v152
	v_add_f32_e32 v152, v95, v152
	s_waitcnt lgkmcnt(3)
	v_mfma_f32_32x32x16_bf16 v[96:111], v[164:167], v[128:131], v[96:111]
	s_waitcnt lgkmcnt(0)
	v_mfma_f32_32x32x16_bf16 v[112:127], v[168:171], v[182:185], v[112:127]
	v_add_u32_e32 v245, v235, v228
	v_mov_b32_e32 v153, v152
	ds_read_b128 v[164:167], v245 offset:12288
	ds_read_b128 v[206:209], v192 offset:57344
	ds_read_b128 v[210:213], v188 offset:1024
	v_permlane32_swap_b32_e32 v152, v153
	v_add_f32_e32 v251, v152, v153
	v_cvt_pk_bf16_f32 v152, v64, v65
	v_mfma_f32_32x32x16_bf16 v[96:111], v[160:163], v[182:185], v[96:111]
	v_cvt_pk_bf16_f32 v153, v66, v67
	v_cvt_pk_bf16_f32 v154, v68, v69
	v_cvt_pk_bf16_f32 v155, v70, v71
	v_fmac_f32_e32 v251, v180, v250
	v_permlane32_swap_b32_e32 v152, v154
	v_permlane32_swap_b32_e32 v153, v155
	s_waitcnt lgkmcnt(0)
	v_mfma_f32_32x32x16_bf16 v[112:127], v[206:209], v[210:213], v[112:127]
	v_add_u32_e32 v246, v235, v229
	ds_read_b128 v[64:67], v246 offset:12288
	ds_read_b128 v[68:71], v194 offset:57344
	ds_read_b128 v[160:163], v188 offset:2048
	v_cvt_pk_bf16_f32 v156, v72, v73
	v_cvt_pk_bf16_f32 v157, v74, v75
	v_cvt_pk_bf16_f32 v158, v76, v77
	v_cvt_pk_bf16_f32 v159, v78, v79
	v_mfma_f32_32x32x16_bf16 v[96:111], v[164:167], v[210:213], v[96:111]
	v_permlane32_swap_b32_e32 v156, v158
	v_permlane32_swap_b32_e32 v157, v159
	s_waitcnt lgkmcnt(0)
	v_mfma_f32_32x32x16_bf16 v[112:127], v[68:71], v[160:163], v[112:127]
	v_add_u32_e32 v247, v235, v230
	ds_read_b128 v[72:75], v247 offset:12288
	ds_read_b128 v[76:79], v190 offset:57344
	ds_read_b128 v[164:167], v188 offset:3072
	v_cvt_pk_bf16_f32 v80, v80, v81
	v_cvt_pk_bf16_f32 v81, v82, v83
	v_cvt_pk_bf16_f32 v82, v84, v85
	v_cvt_pk_bf16_f32 v83, v86, v87
	v_mfma_f32_32x32x16_bf16 v[96:111], v[64:67], v[160:163], v[96:111]
	v_permlane32_swap_b32_e32 v80, v82
	v_permlane32_swap_b32_e32 v81, v83
	s_waitcnt lgkmcnt(0)
; #define PV_SM(o, vb, a0, a1, a2, a3, q0, q1, m, mn, al) do { if constexpr ((CF::ND0 == 8 || ATT_B_PV) && !MASK) pv_sm<CF>(o, vb, a0, a1, a2, a3, q0, q1, m, mn, al); \
;     else { pv_d0(o, vb, a0, a1, a2, a3); partialSM<CF>(q0, q1, m, mn, al); } } while (0)
; #define PV_SM(o, vb, a0, a1, a2, a3, q0, q1, m, mn, al) do { pv_d0(o, vb, a0, a1, a2, a3); partialSM<CF>(q0, q1, m, mn, al); } while (0)
; #define ATT_SBAR() __builtin_amdgcn_sched_barrier(0)
; #define ATT_QMM(src, g) do { _Pragma("unroll") for (int t = 0; t < 2; ++t) { n0 = __builtin_amdgcn_mfma_f32_32x32x16_bf16(src[2 * t], qr[2 * (g) + t], n0, 0, 0, 0); \
;     n1 = __builtin_amdgcn_mfma_f32_32x32x16_bf16(src[2 * t + 1], qr[2 * (g) + t], n1, 0, 0, 0); } } while (0)
; template <class CF> __device__ __forceinline__ void qk_sm1(f32x16& n0, f32x16& n1, const char* Ks, const bf16x8* qr, const char* qx, int r32, int hi, ...
;     ...
;     else if (g == 9) { ATT_PK4(p1, 8, pa3); asm volatile("" : "+v"(pa3)); }
;     ATT_QMM(g & 1, g);
;     if (g + 1 < 12) { asm volatile("s_waitcnt lgkmcnt(0)" ::: "memory"); ATT_SBAR(); }
;   }
; template <class CF> __device__ __forceinline__ void pv_sm(f32x16* o, int vb, bf16x8 pa0, bf16x8 pa1, bf16x8 pa2, bf16x8 pa3, f32x16& p0, f32x16& p1, float& m_reg, float& mn, float& alpha) {
;   constexpr float C = CF::SCALE * 1.4426950408889634f;
;   s16x4 f[8];
;   pv_reads<0>(vb, f);
;   float pmax = p0[0];
; #pragma unroll
;   for (int r = 1; r < 16; ++r) pmax = fmaxf(pmax, p0[r]);
;   asm volatile("" : "+v"(pmax));
;   pv_mfma4(o[0], f, pa0, pa1, pa2, pa3);
;   pv_reads<1>(vb, f);
; #pragma unroll
;   for (int r = 0; r < 16; ++r) pmax = fmaxf(pmax, p1[r]);
;   { auto rr = __builtin_amdgcn_permlane32_swap(__float_as_uint(pmax), __float_as_uint(pmax), false, false);
;     pmax = fmaxf(__uint_as_float(rr[0]), __uint_as_float(rr[1])); }
;   asm volatile("" : "+v"(pmax));
;   pv_mfma4(o[1], f, pa0, pa1, pa2, pa3);
;   pv_reads<2>(vb, f);
;   if (__builtin_expect(__all(pmax - m_reg <= THR / CF::SCALE), 1)) { mn = m_reg; alpha = 1.f; }
;   else { mn = fmaxf(m_reg, pmax); alpha = __builtin_amdgcn_exp2f((m_reg - mn) * C); m_reg = mn; }
;     ...
;     ATT_SLOAD(SO, (j + SDEPTH) * KVBLK); ATT_SBAR();
;     PV_SM(o, vb0, pa0, pa1, pa2, pa3, pB0, pB1, m_reg, mnB, alB);
	v_mfma_f32_32x32x16_bf16 v[112:127], v[76:79], v[164:167], v[112:127]
	v_add_u32_e32 v248, v235, v231
	ds_read_b128 v[64:67], v248 offset:12288
	ds_read_b128 v[68:71], v193 offset:57344
	ds_read_b128 v[160:163], v188 offset:4096
	v_cvt_pk_bf16_f32 v84, v88, v89
	v_cvt_pk_bf16_f32 v85, v90, v91
	v_cvt_pk_bf16_f32 v86, v92, v93
	v_cvt_pk_bf16_f32 v87, v94, v95
	v_mfma_f32_32x32x16_bf16 v[96:111], v[72:75], v[164:167], v[96:111]
	v_permlane32_swap_b32_e32 v84, v86
	v_permlane32_swap_b32_e32 v85, v87
	s_waitcnt lgkmcnt(0)
	v_mfma_f32_32x32x16_bf16 v[112:127], v[68:71], v[160:163], v[112:127]
	v_add_u32_e32 v249, v235, v232
	ds_read_b128 v[68:71], v249 offset:12288
	ds_read_b128 v[72:75], v191 offset:57344
	ds_read_b128 v[76:79], v188 offset:5120
	v_mfma_f32_32x32x16_bf16 v[96:111], v[64:67], v[160:163], v[96:111]
	s_waitcnt lgkmcnt(0)
	v_mfma_f32_32x32x16_bf16 v[112:127], v[72:75], v[76:79], v[112:127]
	v_mfma_f32_32x32x16_bf16 v[96:111], v[68:71], v[76:79], v[96:111]
	v_lshl_add_u64 v[180:181], v[178:179], 0, s[8:9]
	s_mov_b32 s0, 0x3f900000
	v_add_co_u32_e32 v64, vcc, s0, v180
	s_mov_b32 s0, 0x3f940000
	s_nop 0
	v_addc_co_u32_e32 v65, vcc, 0, v181, vcc
	v_add_co_u32_e32 v66, vcc, s0, v180
	v_lshl_add_u64 v[182:183], v[176:177], 0, s[8:9]
	s_nop 0
	v_addc_co_u32_e32 v67, vcc, 0, v181, vcc
	global_load_dwordx4 v[88:91], v[64:65], off offset:256
	global_load_dwordx4 v[92:95], v[66:67], off offset:256
	v_add_co_u32_e32 v64, vcc, s85, v182
	s_mov_b32 s0, 0x4f8f0000
	s_nop 0
	v_addc_co_u32_e32 v65, vcc, 0, v183, vcc
	v_add_co_u32_e32 v66, vcc, s0, v182
	v_lshl_add_u64 v[184:185], v[174:175], 0, s[8:9]
	s_nop 0
	v_addc_co_u32_e32 v67, vcc, 0, v183, vcc
	global_load_dwordx4 v[160:163], v[64:65], off
	global_load_dwordx4 v[164:167], v[66:67], off
	v_add_co_u32_e32 v64, vcc, s85, v184
	s_nop 1
	v_addc_co_u32_e32 v65, vcc, 0, v185, vcc
	global_load_dwordx4 v[168:171], v[64:65], off offset:256
	ds_read_b64_tr_b16 v[64:65], v187 offset:0
	ds_read_b64_tr_b16 v[66:67], v187 offset:0x800
	ds_read_b64_tr_b16 v[68:69], v187 offset:0x1000
	ds_read_b64_tr_b16 v[70:71], v187 offset:0x1800
	ds_read_b64_tr_b16 v[72:73], v187 offset:0x2000
	ds_read_b64_tr_b16 v[74:75], v187 offset:0x2800
	ds_read_b64_tr_b16 v[76:77], v187 offset:0x3000
	ds_read_b64_tr_b16 v[78:79], v187 offset:0x3800
	s_waitcnt lgkmcnt(6)
	v_mfma_f32_32x32x16_bf16 v[0:15], v[152:155], v[64:67], v[0:15]
	v_max_f32_e32 v206, v112, v113
	v_max3_f32 v206, v206, v114, v115
	v_max3_f32 v206, v206, v116, v117
	v_max3_f32 v206, v206, v118, v119
	v_max3_f32 v206, v206, v120, v121
	s_waitcnt lgkmcnt(4)
	v_mfma_f32_32x32x16_bf16 v[0:15], v[156:159], v[68:71], v[0:15]
	v_max3_f32 v206, v206, v122, v123
	v_max3_f32 v206, v206, v124, v125
	v_max3_f32 v206, v206, v126, v127
	ds_read_b64_tr_b16 v[64:65], v187 offset:0x200
	ds_read_b64_tr_b16 v[66:67], v187 offset:0xa00
	ds_read_b64_tr_b16 v[68:69], v187 offset:0x1200
	s_waitcnt lgkmcnt(5)
	v_mfma_f32_32x32x16_bf16 v[0:15], v[80:83], v[72:75], v[0:15]
	ds_read_b64_tr_b16 v[70:71], v187 offset:0x1a00
	ds_read_b64_tr_b16 v[72:73], v187 offset:0x2200
	ds_read_b64_tr_b16 v[74:75], v187 offset:0x2a00
	s_waitcnt lgkmcnt(6)
	v_mfma_f32_32x32x16_bf16 v[0:15], v[84:87], v[76:79], v[0:15]
	ds_read_b64_tr_b16 v[76:77], v187 offset:0x3200
	ds_read_b64_tr_b16 v[78:79], v187 offset:0x3a00
	s_waitcnt lgkmcnt(6)
	v_mfma_f32_32x32x16_bf16 v[48:63], v[152:155], v[64:67], v[48:63]
	v_max3_f32 v206, v206, v96, v97
	v_max3_f32 v206, v206, v98, v99
	v_max3_f32 v206, v206, v100, v101
	v_max3_f32 v206, v206, v102, v103
	v_max3_f32 v206, v206, v104, v105
	v_max3_f32 v206, v206, v106, v107
	v_max3_f32 v206, v206, v108, v109
	s_waitcnt lgkmcnt(4)
	v_mfma_f32_32x32x16_bf16 v[48:63], v[156:159], v[68:71], v[48:63]
	v_max3_f32 v206, v206, v110, v111
	v_mov_b32_e32 v207, v206
	s_nop 1
	v_permlane32_swap_b32_e32 v206, v207
	v_max_f32_e32 v218, v206, v207
	s_waitcnt lgkmcnt(2)
	v_mfma_f32_32x32x16_bf16 v[48:63], v[80:83], v[72:75], v[48:63]
	ds_read_b64_tr_b16 v[64:65], v187 offset:0x400
	ds_read_b64_tr_b16 v[66:67], v187 offset:0xc00
	ds_read_b64_tr_b16 v[68:69], v187 offset:0x1400
	ds_read_b64_tr_b16 v[70:71], v187 offset:0x1c00
	ds_read_b64_tr_b16 v[206:207], v187 offset:0x2400
	ds_read_b64_tr_b16 v[208:209], v187 offset:0x2c00
	s_waitcnt lgkmcnt(6)
	v_mfma_f32_32x32x16_bf16 v[48:63], v[84:87], v[76:79], v[48:63]
	ds_read_b64_tr_b16 v[210:211], v187 offset:0x3400
	ds_read_b64_tr_b16 v[212:213], v187 offset:0x3c00
	s_waitcnt lgkmcnt(6)
	v_mfma_f32_32x32x16_bf16 v[32:47], v[152:155], v[64:67], v[32:47]
	v_sub_f32_e32 v72, v218, v233
	v_cmp_ge_f32_e32 vcc, s63, v72
	v_max_f32_e32 v72, v233, v218
	v_sub_f32_e32 v73, v233, v72
	v_mul_f32_e32 v73, 0x3dd53b94, v73
	s_waitcnt lgkmcnt(4)
	v_mfma_f32_32x32x16_bf16 v[32:47], v[156:159], v[68:71], v[32:47]
	s_cmp_eq_u64 vcc, exec
	v_exp_f32_e32 v73, v73
	s_cselect_b64 vcc, -1, 0
	v_cndmask_b32_e32 v233, v72, v233, vcc
	v_mul_f32_e32 v218, 0xbdd53b94, v233
	v_cndmask_b32_e64 v252, v73, 1.0, vcc
	v_pk_fma_f32 v[78:79], v[126:127], s[84:85], v[218:219] op_sel_hi:[1,0,0]
	s_waitcnt lgkmcnt(2)
; #define ATT_SYNC() __syncthreads()
; #define ATT_SWRITE(b, i) do { *(bf16x8*)(V_lds + (b) * SHM_V + vst0) = sr_[i].vs0; *(bf16x8*)(V_lds + (b) * SHM_V + vst1) = sr_[i].vs1; \
;     *(bf16x8*)(K_lds + (b) * SHM_K + kst0) = sr_[i].ks0; *(bf16x8*)(K_lds + (b) * SHM_K + kst1) = sr_[i].ks1; if constexpr (ND0 == 12) *(bf16x8*)(K_lds + (b) * SHM_K + kst2) = sr_[i].ks2; } while (0)
; #define ATT_SWAIT() do { if constexpr (SDEPTH == 2) { if constexpr (ND0 == 12) asm volatile("s_waitcnt vmcnt(5)" ::: "memory"); else asm volatile("s_waitcnt vmcnt(4)" ::: "memory"); } else asm volatile("s_waitcnt vmcnt(0)" ::: "memory"); } while (0)
; #define ATT_RESC(al) do { if (__any((al) < 1.f)) { if (hi == 0) al_l[r32] = (al); asm volatile("s_waitcnt lgkmcnt(0)" ::: "memory"); \
;     _Pragma("unroll") for (int d = 0; d < 4; ++d) _Pragma("unroll") for (int r = 0; r < 16; ++r) o[d][r] *= al_l[crow(r, hi)]; } } while (0)
; #define ATT_SWRITE(b, i) do { *(bf16x8*)(V_lds + (b) * SHM_V + vst0) = sr_[i].vs0; *(bf16x8*)(V_lds + (b) * SHM_V + vst1) = sr_[i].vs1; \
;     *(bf16x8*)(K_lds + (b) * SHM_K + kst0) = sr_[i].ks0; *(bf16x8*)(K_lds + (b) * SHM_K + kst1) = sr_[i].ks1; if constexpr (ND0 == 12) *(bf16x8*)(K_lds + (b) * SHM_K + kst2) = sr_[i].ks2; } while (0)
; #define ATT_SWAIT() do { if constexpr (ND0 == 12) asm volatile("s_waitcnt vmcnt(5)" ::: "memory"); else asm volatile("s_waitcnt vmcnt(4)" ::: "memory"); } while (0)
; template <class CF> __device__ __forceinline__ void pv_sm(f32x16* o, int vb, bf16x8 pa0, bf16x8 pa1, bf16x8 pa2, bf16x8 pa3, f32x16& p0, f32x16& p1, float& m_reg, float& mn, float& alpha) {
;     ...
; #pragma unroll
;   for (int r = 0; r < 16; ++r) p0[r] = fmaf(p0[r], C, mnC);
; #pragma unroll
;   for (int r = 0; r < 16; ++r) p1[r] = fmaf(p1[r], C, mnC);
;   asm volatile("" : "+v"(p0), "+v"(p1));
;   pv_mfma4(o[2], f, pa0, pa1, pa2, pa3);
;   pv_reads<3>(vb, f);
; #pragma unroll
;   for (int r = 0; r < 16; ++r) p0[r] = __builtin_amdgcn_exp2f(p0[r]);
;   asm volatile("" : "+v"(p0));
;   pv_mfma4(o[3], f, pa0, pa1, pa2, pa3);
; }
;     ...
;     ATT_SYNC(); ATT_SWAIT(); ATT_SWRITE(0, SE);
;     ATT_RESC(alB); ATT_SYNC();
	v_mfma_f32_32x32x16_bf16 v[32:47], v[80:83], v[206:209], v[32:47]
	v_fma_f32 v76, v124, s84, v218
	v_fma_f32 v77, v125, s84, v218
	v_fma_f32 v74, v122, s84, v218
	v_fma_f32 v75, v123, s84, v218
	v_fma_f32 v72, v120, s84, v218
	v_fma_f32 v73, v121, s84, v218
	v_pk_fma_f32 v[70:71], v[118:119], s[84:85], v[218:219] op_sel_hi:[1,0,0]
	v_pk_fma_f32 v[68:69], v[116:117], s[84:85], v[218:219] op_sel_hi:[1,0,0]
	v_pk_fma_f32 v[66:67], v[114:115], s[84:85], v[218:219] op_sel_hi:[1,0,0]
	v_pk_fma_f32 v[64:65], v[112:113], s[84:85], v[218:219] op_sel_hi:[1,0,0]
	v_pk_fma_f32 v[126:127], v[110:111], s[84:85], v[218:219] op_sel_hi:[1,0,0]
	v_pk_fma_f32 v[124:125], v[108:109], s[84:85], v[218:219] op_sel_hi:[1,0,0]
	v_pk_fma_f32 v[122:123], v[106:107], s[84:85], v[218:219] op_sel_hi:[1,0,0]
	v_pk_fma_f32 v[120:121], v[104:105], s[84:85], v[218:219] op_sel_hi:[1,0,0]
	v_pk_fma_f32 v[118:119], v[102:103], s[84:85], v[218:219] op_sel_hi:[1,0,0]
	v_pk_fma_f32 v[116:117], v[100:101], s[84:85], v[218:219] op_sel_hi:[1,0,0]
	v_pk_fma_f32 v[114:115], v[98:99], s[84:85], v[218:219] op_sel_hi:[1,0,0]
	v_pk_fma_f32 v[112:113], v[96:97], s[84:85], v[218:219] op_sel_hi:[1,0,0]
	s_waitcnt lgkmcnt(0)
	v_mfma_f32_32x32x16_bf16 v[32:47], v[84:87], v[210:213], v[32:47]
	s_waitcnt vmcnt(0)
	ds_write_b128 v197, v[160:163] offset:32768
	ds_write_b128 v197, v[164:167] offset:45056
	ds_write_b128 v199, v[168:171] offset:32768
	ds_read_b64_tr_b16 v[104:105], v187 offset:0x600
	ds_read_b64_tr_b16 v[106:107], v187 offset:0xe00
	ds_read_b64_tr_b16 v[206:207], v187 offset:0x1600
	ds_read_b64_tr_b16 v[208:209], v187 offset:0x1e00
	ds_read_b64_tr_b16 v[210:211], v187 offset:0x2600
	ds_read_b64_tr_b16 v[212:213], v187 offset:0x2e00
	ds_read_b64_tr_b16 v[218:219], v187 offset:0x3600
	ds_read_b64_tr_b16 v[220:221], v187 offset:0x3e00
	s_waitcnt lgkmcnt(6)
	v_mfma_f32_32x32x16_bf16 v[16:31], v[152:155], v[104:107], v[16:31]
	v_exp_f32_e32 v96, v64
	v_exp_f32_e32 v97, v65
	v_exp_f32_e32 v98, v66
	v_exp_f32_e32 v99, v67
	v_exp_f32_e32 v100, v68
	v_exp_f32_e32 v101, v69
	v_exp_f32_e32 v102, v70
	s_waitcnt lgkmcnt(4)
	v_mfma_f32_32x32x16_bf16 v[16:31], v[156:159], v[206:209], v[16:31]
	v_exp_f32_e32 v103, v71
	v_exp_f32_e32 v104, v72
	v_exp_f32_e32 v105, v73
	v_exp_f32_e32 v106, v74
	v_exp_f32_e32 v107, v75
	v_exp_f32_e32 v108, v76
	v_exp_f32_e32 v109, v77
	s_waitcnt lgkmcnt(2)
	v_mfma_f32_32x32x16_bf16 v[16:31], v[80:83], v[210:213], v[16:31]
	v_exp_f32_e32 v110, v78
	v_exp_f32_e32 v111, v79
	s_waitcnt lgkmcnt(0)
	s_barrier
	ds_write_b128 v195, v[88:91]
	ds_write_b128 v196, v[92:95]
	v_mfma_f32_32x32x16_bf16 v[16:31], v[84:87], v[218:221], v[16:31]
	v_cmp_gt_f32_e32 vcc, 1.0, v252
	s_cbranch_vccz .LBB0_1729
	s_and_saveexec_b64 s[12:13], s[4:5]
	ds_write_b32 v224, v252 offset:128
	s_or_b64 exec, exec, s[12:13]
	s_waitcnt lgkmcnt(0)
	v_add_u32_e32 v76, v186, v204
	ds_read_b128 v[64:67], v76 offset:224
	ds_read_b128 v[68:71], v76 offset:192
	ds_read_b128 v[72:75], v76 offset:160
	ds_read_b128 v[76:79], v76 offset:128
	s_waitcnt lgkmcnt(3)
	v_pk_mul_f32 v[12:13], v[12:13], v[64:65]
	s_waitcnt lgkmcnt(2)
	v_pk_mul_f32 v[8:9], v[8:9], v[68:69]
	s_waitcnt lgkmcnt(1)
	v_pk_mul_f32 v[4:5], v[4:5], v[72:73]
	v_pk_mul_f32 v[14:15], v[14:15], v[66:67]
	v_pk_mul_f32 v[10:11], v[10:11], v[70:71]
	v_pk_mul_f32 v[6:7], v[6:7], v[74:75]
	s_waitcnt lgkmcnt(0)
	v_pk_mul_f32 v[2:3], v[2:3], v[78:79]
	v_pk_mul_f32 v[0:1], v[0:1], v[76:77]
	v_pk_mul_f32 v[60:61], v[60:61], v[64:65]
	v_pk_mul_f32 v[56:57], v[56:57], v[68:69]
	v_pk_mul_f32 v[52:53], v[52:53], v[72:73]
	v_pk_mul_f32 v[62:63], v[62:63], v[66:67]
	v_pk_mul_f32 v[58:59], v[58:59], v[70:71]
	v_pk_mul_f32 v[54:55], v[54:55], v[74:75]
	v_pk_mul_f32 v[50:51], v[50:51], v[78:79]
	v_pk_mul_f32 v[48:49], v[48:49], v[76:77]
	v_pk_mul_f32 v[44:45], v[44:45], v[64:65]
	v_pk_mul_f32 v[40:41], v[40:41], v[68:69]
	v_pk_mul_f32 v[36:37], v[36:37], v[72:73]
	v_pk_mul_f32 v[46:47], v[46:47], v[66:67]
	v_pk_mul_f32 v[42:43], v[42:43], v[70:71]
	v_pk_mul_f32 v[38:39], v[38:39], v[74:75]
	v_pk_mul_f32 v[34:35], v[34:35], v[78:79]
	v_pk_mul_f32 v[32:33], v[32:33], v[76:77]
	v_pk_mul_f32 v[28:29], v[28:29], v[64:65]
	v_pk_mul_f32 v[24:25], v[24:25], v[68:69]
	v_pk_mul_f32 v[20:21], v[20:21], v[72:73]
	v_pk_mul_f32 v[30:31], v[30:31], v[66:67]
	v_pk_mul_f32 v[26:27], v[26:27], v[70:71]
	v_pk_mul_f32 v[22:23], v[22:23], v[74:75]
	v_pk_mul_f32 v[18:19], v[18:19], v[78:79]
	v_pk_mul_f32 v[16:17], v[16:17], v[76:77]
; #define ATT_SBAR() __builtin_amdgcn_sched_barrier(0)
; #define ATT_QRD(dst, g) do { _Pragma("unroll") for (int t = 0; t < 2; ++t) { const int cb = ((2 * (g) + t) * 16 + hi * 8) * 2; \
;     dst[2 * t] = *reinterpret_cast<const bf16x8*>(kr + (cb ^ sw)); dst[2 * t + 1] = *reinterpret_cast<const bf16x8*>(kr + 32 * CF::KPITCH + (cb ^ sw)); } } while (0)
; template <class CF> __device__ __forceinline__ void qk_sm1(f32x16& n0, f32x16& n1, const char* Ks, const bf16x8* qr, const char* qx, int r32, int hi, ...
;   static_assert(CF::ND0 == 12, "qk_sm1: 12 d0 steps");
;   n0 = f32x16{}; n1 = f32x16{};
;   const char* kr = Ks + r32 * CF::KPITCH; const int sw = (r32 & CF::KSWM) << 4;
;   bf16x8 kf[2][2], qf[2];
;     ...
;   ATT_QRD(0, 0); asm volatile("s_waitcnt lgkmcnt(0)" ::: "memory"); ATT_SBAR();
;   float ps = 0;
; #pragma unroll
;   for (int g = 0; g < 12; ++g) {
;     if (g + 1 < 12) ATT_QRD((g + 1) & 1, g + 1);
;     if (g < 2) {
; #pragma unroll
;       for (int r = 0; r < 8; ++r) p1[8 * g + r] = __builtin_amdgcn_exp2f(p1[8 * g + r]);
;       if (g == 1) asm volatile("" : "+v"(p1)); }
;     else if (g < 6) {
; #pragma unroll
;       for (int r = 0; r < 8; ++r) ps += (g < 4 ? p0[8 * (g - 2) + r] : p1[8 * (g - 4) + r]);
;       asm volatile("" : "+v"(ps)); }
;     else if (g == 6) {
;       { auto rr = __builtin_amdgcn_permlane32_swap(__float_as_uint(ps), __float_as_uint(ps), false, false);
;         ps = __uint_as_float(rr[0]) + __uint_as_float(rr[1]); }
;       l_reg = l_reg * alpha + ps;
;       ATT_PK4(p0, 0, pa0);
;       asm volatile("" : "+v"(l_reg), "+v"(pa0)); }
;     else if (g == 7) { ATT_PK4(p0, 8, pa1); asm volatile("" : "+v"(pa1)); }
;     else if (g == 8) { ATT_PK4(p1, 0, pa2); asm volatile("" : "+v"(pa2)); }
;     else if (g == 9) { ATT_PK4(p1, 8, pa3); asm volatile("" : "+v"(pa3)); }
;     ATT_QMM(g & 1, g);
;     if (g + 1 < 12) { asm volatile("s_waitcnt lgkmcnt(0)" ::: "memory"); ATT_SBAR(); }
;   }
;     ...
;     ATT_SBAR(); if constexpr (QKSPLIT) qk_sm<CF>(pA0, pA1, K_lds, qr, r32, hi, pB0, pB1, alB, l_reg, pa0, pa1, pa2, pa3);
;     else if constexpr (QK1) qk_sm1<CF>(pA0, pA1, K_lds, qr, qx, r32, hi, pB0, pB1, alB, l_reg, pa0, pa1, pa2, pa3);
;     else { qkt<CF>(pA0, pA1, K_lds, qr, qx, r32, hi); if constexpr (MASK) bandmask(pA0, pA1, (j + 1) * KVBLK, qi, hi);
;     finishSM(pB0, pB1, alB, l_reg, pa0, pa1, pa2, pa3); } ATT_SBAR();
.LBB0_1729:
	ds_read_b128 v[64:67], v237 offset:32768
	ds_read_b128 v[68:71], v237 offset:45056
	s_waitcnt lgkmcnt(1)
	v_mfma_f32_32x32x16_bf16 v[80:95], v[64:67], v[148:151], 0
	ds_read_b128 v[152:155], v215 offset:32768
	ds_read_b128 v[156:159], v215 offset:45056
	v_exp_f32_e32 v112, v112
	v_exp_f32_e32 v113, v113
	v_exp_f32_e32 v114, v114
	v_exp_f32_e32 v115, v115
	v_exp_f32_e32 v116, v116
	s_waitcnt lgkmcnt(2)
	v_mfma_f32_32x32x16_bf16 v[64:79], v[68:71], v[148:151], 0
	v_exp_f32_e32 v117, v117
	v_exp_f32_e32 v118, v118
	v_exp_f32_e32 v119, v119
	s_waitcnt lgkmcnt(1)
	v_mfma_f32_32x32x16_bf16 v[80:95], v[152:155], v[144:147], v[80:95]
	ds_read_b128 v[152:155], v203 offset:32768
	ds_read_b128 v[160:163], v203 offset:45056
	v_exp_f32_e32 v120, v120
	v_exp_f32_e32 v121, v121
	v_exp_f32_e32 v122, v122
	v_exp_f32_e32 v123, v123
	v_exp_f32_e32 v124, v124
	v_exp_f32_e32 v125, v125
	s_waitcnt lgkmcnt(2)
	v_mfma_f32_32x32x16_bf16 v[64:79], v[156:159], v[144:147], v[64:79]
	v_exp_f32_e32 v126, v126
	v_exp_f32_e32 v127, v127
	v_add_f32_e32 v168, v97, v96
	v_add_f32_e32 v168, v98, v168
	s_waitcnt lgkmcnt(1)
	v_mfma_f32_32x32x16_bf16 v[80:95], v[152:155], v[140:143], v[80:95]
	v_add_f32_e32 v152, v99, v168
	v_add_f32_e32 v152, v100, v152
	v_add_f32_e32 v152, v101, v152
	ds_read_b128 v[156:159], v214 offset:32768
	ds_read_b128 v[164:167], v214 offset:45056
	v_add_f32_e32 v152, v102, v152
	v_add_f32_e32 v168, v103, v152
	s_waitcnt lgkmcnt(2)
	v_mfma_f32_32x32x16_bf16 v[64:79], v[160:163], v[140:143], v[64:79]
	v_add_f32_e32 v168, v104, v168
	v_add_f32_e32 v168, v105, v168
	v_add_f32_e32 v168, v106, v168
	s_waitcnt lgkmcnt(1)
	v_mfma_f32_32x32x16_bf16 v[80:95], v[156:159], v[136:139], v[80:95]
	v_add_f32_e32 v156, v107, v168
	v_add_f32_e32 v156, v108, v156
	v_add_f32_e32 v156, v109, v156
	ds_read_b128 v[152:155], v202 offset:32768
	ds_read_b128 v[160:163], v202 offset:45056
	v_add_f32_e32 v156, v110, v156
	v_add_f32_e32 v168, v111, v156
	s_waitcnt lgkmcnt(2)
	v_mfma_f32_32x32x16_bf16 v[64:79], v[164:167], v[136:139], v[64:79]
	v_add_f32_e32 v168, v112, v168
	v_add_f32_e32 v168, v113, v168
	v_add_f32_e32 v168, v114, v168
	s_waitcnt lgkmcnt(1)
	v_mfma_f32_32x32x16_bf16 v[80:95], v[152:155], v[132:135], v[80:95]
	v_add_f32_e32 v152, v115, v168
	v_add_f32_e32 v152, v116, v152
	v_add_f32_e32 v152, v117, v152
	ds_read_b128 v[156:159], v201 offset:32768
	ds_read_b128 v[164:167], v201 offset:45056
	v_add_f32_e32 v152, v118, v152
	v_add_f32_e32 v152, v119, v152
	s_waitcnt lgkmcnt(2)
	v_mfma_f32_32x32x16_bf16 v[64:79], v[160:163], v[132:135], v[64:79]
	v_add_f32_e32 v152, v120, v152
	v_add_f32_e32 v152, v121, v152
	v_add_f32_e32 v152, v122, v152
	s_waitcnt lgkmcnt(1)
	v_mfma_f32_32x32x16_bf16 v[80:95], v[156:159], v[128:131], v[80:95]
	v_add_f32_e32 v152, v123, v152
	v_add_f32_e32 v152, v124, v152
	ds_read_b128 v[160:163], v198 offset:45056
	ds_read_b128 v[168:171], v198 offset:32768
	ds_read_b128 v[206:209], v188
	v_add_f32_e32 v152, v125, v152
	v_add_f32_e32 v152, v126, v152
	v_add_f32_e32 v152, v127, v152
	s_waitcnt lgkmcnt(3)
	v_mfma_f32_32x32x16_bf16 v[64:79], v[164:167], v[128:131], v[64:79]
	s_waitcnt lgkmcnt(0)
	v_mfma_f32_32x32x16_bf16 v[80:95], v[168:171], v[206:209], v[80:95]
	v_mov_b32_e32 v153, v152
	ds_read_b128 v[164:167], v192 offset:45056
	ds_read_b128 v[210:213], v192 offset:32768
	ds_read_b128 v[218:221], v188 offset:1024
	v_permlane32_swap_b32_e32 v152, v153
	v_add_f32_e32 v250, v152, v153
	v_cvt_pk_bf16_f32 v152, v96, v97
	v_cvt_pk_bf16_f32 v153, v98, v99
	v_mfma_f32_32x32x16_bf16 v[64:79], v[160:163], v[206:209], v[64:79]
	v_cvt_pk_bf16_f32 v154, v100, v101
	v_cvt_pk_bf16_f32 v155, v102, v103
	v_fmac_f32_e32 v250, v251, v252
	v_permlane32_swap_b32_e32 v152, v154
	v_permlane32_swap_b32_e32 v153, v155
	s_waitcnt lgkmcnt(0)
	v_mfma_f32_32x32x16_bf16 v[80:95], v[210:213], v[218:221], v[80:95]
	ds_read_b128 v[96:99], v194 offset:45056
	ds_read_b128 v[100:103], v194 offset:32768
	ds_read_b128 v[160:163], v188 offset:2048
	v_cvt_pk_bf16_f32 v156, v104, v105
	v_cvt_pk_bf16_f32 v157, v106, v107
	v_cvt_pk_bf16_f32 v158, v108, v109
	v_cvt_pk_bf16_f32 v159, v110, v111
	s_nop 0
	v_permlane32_swap_b32_e32 v156, v158
	v_mfma_f32_32x32x16_bf16 v[64:79], v[164:167], v[218:221], v[64:79]
	v_permlane32_swap_b32_e32 v157, v159
	s_waitcnt lgkmcnt(0)
	v_mfma_f32_32x32x16_bf16 v[80:95], v[100:103], v[160:163], v[80:95]
	ds_read_b128 v[104:107], v190 offset:45056
	ds_read_b128 v[108:111], v190 offset:32768
	ds_read_b128 v[164:167], v188 offset:3072
	v_cvt_pk_bf16_f32 v112, v112, v113
	v_cvt_pk_bf16_f32 v113, v114, v115
	v_cvt_pk_bf16_f32 v114, v116, v117
	v_cvt_pk_bf16_f32 v115, v118, v119
	s_nop 0
	v_permlane32_swap_b32_e32 v112, v114
	v_mfma_f32_32x32x16_bf16 v[64:79], v[96:99], v[160:163], v[64:79]
	v_permlane32_swap_b32_e32 v113, v115
	s_waitcnt lgkmcnt(0)
	v_mfma_f32_32x32x16_bf16 v[80:95], v[108:111], v[164:167], v[80:95]
	ds_read_b128 v[96:99], v193 offset:45056
	ds_read_b128 v[100:103], v193 offset:32768
	ds_read_b128 v[160:163], v188 offset:4096
	v_cvt_pk_bf16_f32 v116, v120, v121
	v_cvt_pk_bf16_f32 v117, v122, v123
	v_cvt_pk_bf16_f32 v118, v124, v125
	v_cvt_pk_bf16_f32 v119, v126, v127
	s_nop 0
	v_permlane32_swap_b32_e32 v116, v118
	v_mfma_f32_32x32x16_bf16 v[64:79], v[104:107], v[164:167], v[64:79]
	v_permlane32_swap_b32_e32 v117, v119
	s_waitcnt lgkmcnt(0)
	v_mfma_f32_32x32x16_bf16 v[80:95], v[100:103], v[160:163], v[80:95]
	ds_read_b128 v[100:103], v191 offset:45056
	ds_read_b128 v[104:107], v191 offset:32768
	ds_read_b128 v[108:111], v188 offset:5120
	v_mfma_f32_32x32x16_bf16 v[64:79], v[96:99], v[160:163], v[64:79]
	s_waitcnt lgkmcnt(0)
; #define PV_SM(o, vb, a0, a1, a2, a3, q0, q1, m, mn, al) do { if constexpr ((CF::ND0 == 8 || ATT_B_PV) && !MASK) pv_sm<CF>(o, vb, a0, a1, a2, a3, q0, q1, m, mn, al); \
;     else { pv_d0(o, vb, a0, a1, a2, a3); partialSM<CF>(q0, q1, m, mn, al); } } while (0)
; #define PV_SM(o, vb, a0, a1, a2, a3, q0, q1, m, mn, al) do { pv_d0(o, vb, a0, a1, a2, a3); partialSM<CF>(q0, q1, m, mn, al); } while (0)
; #define ATT_SBAR() __builtin_amdgcn_sched_barrier(0)
; #define ATT_SYNC() __syncthreads()
; template <class CF> __device__ __forceinline__ void pv_sm(f32x16* o, int vb, bf16x8 pa0, bf16x8 pa1, bf16x8 pa2, bf16x8 pa3, f32x16& p0, f32x16& p1, float& m_reg, float& mn, float& alpha) {
;   constexpr float C = CF::SCALE * 1.4426950408889634f;
;   s16x4 f[8];
;   pv_reads<0>(vb, f);
;   float pmax = p0[0];
; #pragma unroll
;   for (int r = 1; r < 16; ++r) pmax = fmaxf(pmax, p0[r]);
;   asm volatile("" : "+v"(pmax));
;   pv_mfma4(o[0], f, pa0, pa1, pa2, pa3);
;   pv_reads<1>(vb, f);
; #pragma unroll
;   for (int r = 0; r < 16; ++r) pmax = fmaxf(pmax, p1[r]);
;   { auto rr = __builtin_amdgcn_permlane32_swap(__float_as_uint(pmax), __float_as_uint(pmax), false, false);
;     pmax = fmaxf(__uint_as_float(rr[0]), __uint_as_float(rr[1])); }
;   asm volatile("" : "+v"(pmax));
;   pv_mfma4(o[1], f, pa0, pa1, pa2, pa3);
;   pv_reads<2>(vb, f);
;   if (__builtin_expect(__all(pmax - m_reg <= THR / CF::SCALE), 1)) { mn = m_reg; alpha = 1.f; }
;   else { mn = fmaxf(m_reg, pmax); alpha = __builtin_amdgcn_exp2f((m_reg - mn) * C); m_reg = mn; }
;   const float mnC = -mn * C;
; #pragma unroll
;   for (int r = 0; r < 16; ++r) p0[r] = fmaf(p0[r], C, mnC);
; #pragma unroll
;   for (int r = 0; r < 16; ++r) p1[r] = fmaf(p1[r], C, mnC);
;   asm volatile("" : "+v"(p0), "+v"(p1));
;   pv_mfma4(o[2], f, pa0, pa1, pa2, pa3);
;   pv_reads<3>(vb, f);
; #pragma unroll
;   for (int r = 0; r < 16; ++r) p0[r] = __builtin_amdgcn_exp2f(p0[r]);
;   asm volatile("" : "+v"(p0));
;   pv_mfma4(o[3], f, pa0, pa1, pa2, pa3);
; }
;     ...
;     if (SDEPTH == 1 || j + 3 < NT) ATT_SLOAD(SE, (j + 1 + SDEPTH) * KVBLK); ATT_SBAR();
;     PV_SM(o, vb0 + SHM_V, pa0, pa1, pa2, pa3, pA0, pA1, m_reg, mnA, alA);
;     ATT_SYNC(); ATT_SWAIT(); ATT_SWRITE(1, SO);
;     ATT_RESC(alA); ATT_SYNC();
	v_mfma_f32_32x32x16_bf16 v[80:95], v[104:107], v[108:111], v[80:95]
	v_mfma_f32_32x32x16_bf16 v[64:79], v[100:103], v[108:111], v[64:79]
	s_mov_b32 s0, 0x3f980000
	v_add_co_u32_e32 v96, vcc, s0, v180
	s_mov_b32 s0, 0x3f9c0000
	s_nop 0
	v_addc_co_u32_e32 v97, vcc, 0, v181, vcc
	v_add_co_u32_e32 v98, vcc, s0, v180
	s_mov_b32 s0, 0x4f950000
	s_nop 0
	v_addc_co_u32_e32 v99, vcc, 0, v181, vcc
	global_load_dwordx4 v[120:123], v[96:97], off offset:256
	global_load_dwordx4 v[124:127], v[98:99], off offset:256
	v_add_co_u32_e32 v96, vcc, s61, v182
	s_nop 1
	v_addc_co_u32_e32 v97, vcc, 0, v183, vcc
	v_add_co_u32_e32 v98, vcc, s0, v182
	s_nop 1
	v_addc_co_u32_e32 v99, vcc, 0, v183, vcc
	global_load_dwordx4 v[160:163], v[96:97], off
	global_load_dwordx4 v[164:167], v[98:99], off
	v_add_co_u32_e32 v96, vcc, s61, v184
	s_nop 1
	v_addc_co_u32_e32 v97, vcc, 0, v185, vcc
	global_load_dwordx4 v[168:171], v[96:97], off offset:256
	ds_read_b64_tr_b16 v[96:97], v189 offset:0
	ds_read_b64_tr_b16 v[98:99], v189 offset:0x800
	ds_read_b64_tr_b16 v[100:101], v189 offset:0x1000
	ds_read_b64_tr_b16 v[102:103], v189 offset:0x1800
	ds_read_b64_tr_b16 v[104:105], v189 offset:0x2000
	ds_read_b64_tr_b16 v[106:107], v189 offset:0x2800
	ds_read_b64_tr_b16 v[108:109], v189 offset:0x3000
	ds_read_b64_tr_b16 v[110:111], v189 offset:0x3800
	s_waitcnt lgkmcnt(6)
	v_mfma_f32_32x32x16_bf16 v[0:15], v[152:155], v[96:99], v[0:15]
	v_max_f32_e32 v180, v80, v81
	v_max3_f32 v180, v180, v82, v83
	v_max3_f32 v180, v180, v84, v85
	v_max3_f32 v180, v180, v86, v87
	v_max3_f32 v180, v180, v88, v89
	s_waitcnt lgkmcnt(4)
	v_mfma_f32_32x32x16_bf16 v[0:15], v[156:159], v[100:103], v[0:15]
	v_max3_f32 v180, v180, v90, v91
	v_max3_f32 v180, v180, v92, v93
	v_max3_f32 v180, v180, v94, v95
	ds_read_b64_tr_b16 v[96:97], v189 offset:0x200
	ds_read_b64_tr_b16 v[98:99], v189 offset:0xa00
	ds_read_b64_tr_b16 v[100:101], v189 offset:0x1200
	s_waitcnt lgkmcnt(5)
	v_mfma_f32_32x32x16_bf16 v[0:15], v[112:115], v[104:107], v[0:15]
	ds_read_b64_tr_b16 v[102:103], v189 offset:0x1a00
	ds_read_b64_tr_b16 v[104:105], v189 offset:0x2200
	ds_read_b64_tr_b16 v[106:107], v189 offset:0x2a00
	s_waitcnt lgkmcnt(6)
	v_mfma_f32_32x32x16_bf16 v[0:15], v[116:119], v[108:111], v[0:15]
	ds_read_b64_tr_b16 v[108:109], v189 offset:0x3200
	ds_read_b64_tr_b16 v[110:111], v189 offset:0x3a00
	s_waitcnt lgkmcnt(6)
	v_mfma_f32_32x32x16_bf16 v[48:63], v[152:155], v[96:99], v[48:63]
	v_max3_f32 v180, v180, v64, v65
	v_max3_f32 v180, v180, v66, v67
	v_max3_f32 v180, v180, v68, v69
	v_max3_f32 v180, v180, v70, v71
	v_max3_f32 v180, v180, v72, v73
	v_max3_f32 v180, v180, v74, v75
	v_max3_f32 v180, v180, v76, v77
	s_waitcnt lgkmcnt(4)
	v_mfma_f32_32x32x16_bf16 v[48:63], v[156:159], v[100:103], v[48:63]
	v_max3_f32 v180, v180, v78, v79
	v_mov_b32_e32 v181, v180
	s_nop 1
	v_permlane32_swap_b32_e32 v180, v181
	v_max_f32_e32 v180, v180, v181
	s_waitcnt lgkmcnt(2)
	v_mfma_f32_32x32x16_bf16 v[48:63], v[112:115], v[104:107], v[48:63]
	ds_read_b64_tr_b16 v[96:97], v189 offset:0x400
	ds_read_b64_tr_b16 v[98:99], v189 offset:0xc00
	ds_read_b64_tr_b16 v[100:101], v189 offset:0x1400
	ds_read_b64_tr_b16 v[102:103], v189 offset:0x1c00
	ds_read_b64_tr_b16 v[182:183], v189 offset:0x2400
	ds_read_b64_tr_b16 v[184:185], v189 offset:0x2c00
	s_waitcnt lgkmcnt(6)
	v_mfma_f32_32x32x16_bf16 v[48:63], v[116:119], v[108:111], v[48:63]
	ds_read_b64_tr_b16 v[206:207], v189 offset:0x3400
	ds_read_b64_tr_b16 v[208:209], v189 offset:0x3c00
	s_waitcnt lgkmcnt(6)
	v_mfma_f32_32x32x16_bf16 v[32:47], v[152:155], v[96:99], v[32:47]
	v_sub_f32_e32 v104, v180, v233
	v_cmp_ge_f32_e32 vcc, s63, v104
	v_max_f32_e32 v104, v233, v180
	v_sub_f32_e32 v105, v233, v104
	v_mul_f32_e32 v105, 0x3dd53b94, v105
	s_waitcnt lgkmcnt(4)
	v_mfma_f32_32x32x16_bf16 v[32:47], v[156:159], v[100:103], v[32:47]
	s_cmp_eq_u64 vcc, exec
	v_exp_f32_e32 v105, v105
	s_cselect_b64 vcc, -1, 0
	v_cndmask_b32_e32 v233, v104, v233, vcc
	v_mul_f32_e32 v210, 0xbdd53b94, v233
	v_cndmask_b32_e64 v180, v105, 1.0, vcc
	v_pk_fma_f32 v[110:111], v[94:95], s[84:85], v[210:211] op_sel_hi:[1,0,0]
	s_waitcnt lgkmcnt(2)
	v_mfma_f32_32x32x16_bf16 v[32:47], v[112:115], v[182:185], v[32:47]
	v_fma_f32 v108, v92, s84, v210
	v_fma_f32 v109, v93, s84, v210
	v_fma_f32 v106, v90, s84, v210
	v_fma_f32 v107, v91, s84, v210
	v_fma_f32 v104, v88, s84, v210
	v_fma_f32 v105, v89, s84, v210
	v_pk_fma_f32 v[102:103], v[86:87], s[84:85], v[210:211] op_sel_hi:[1,0,0]
	v_pk_fma_f32 v[100:101], v[84:85], s[84:85], v[210:211] op_sel_hi:[1,0,0]
	v_pk_fma_f32 v[98:99], v[82:83], s[84:85], v[210:211] op_sel_hi:[1,0,0]
	v_pk_fma_f32 v[96:97], v[80:81], s[84:85], v[210:211] op_sel_hi:[1,0,0]
	v_pk_fma_f32 v[94:95], v[78:79], s[84:85], v[210:211] op_sel_hi:[1,0,0]
	v_pk_fma_f32 v[92:93], v[76:77], s[84:85], v[210:211] op_sel_hi:[1,0,0]
	v_pk_fma_f32 v[90:91], v[74:75], s[84:85], v[210:211] op_sel_hi:[1,0,0]
	v_pk_fma_f32 v[88:89], v[72:73], s[84:85], v[210:211] op_sel_hi:[1,0,0]
	v_pk_fma_f32 v[86:87], v[70:71], s[84:85], v[210:211] op_sel_hi:[1,0,0]
	v_pk_fma_f32 v[84:85], v[68:69], s[84:85], v[210:211] op_sel_hi:[1,0,0]
	v_pk_fma_f32 v[82:83], v[66:67], s[84:85], v[210:211] op_sel_hi:[1,0,0]
	v_pk_fma_f32 v[80:81], v[64:65], s[84:85], v[210:211] op_sel_hi:[1,0,0]
	s_waitcnt lgkmcnt(0)
	v_mfma_f32_32x32x16_bf16 v[32:47], v[116:119], v[206:209], v[32:47]
	s_waitcnt vmcnt(0)
	ds_write_b128 v197, v[160:163] offset:57344
	ds_write_b128 v234, v[164:167] offset:57344
	ds_write_b128 v199, v[168:171] offset:57344
	ds_read_b64_tr_b16 v[72:73], v189 offset:0x600
	ds_read_b64_tr_b16 v[74:75], v189 offset:0xe00
	ds_read_b64_tr_b16 v[182:183], v189 offset:0x1600
	ds_read_b64_tr_b16 v[184:185], v189 offset:0x1e00
	ds_read_b64_tr_b16 v[206:207], v189 offset:0x2600
	ds_read_b64_tr_b16 v[208:209], v189 offset:0x2e00
	ds_read_b64_tr_b16 v[210:211], v189 offset:0x3600
	ds_read_b64_tr_b16 v[212:213], v189 offset:0x3e00
	s_waitcnt lgkmcnt(6)
	v_mfma_f32_32x32x16_bf16 v[16:31], v[152:155], v[72:75], v[16:31]
	v_exp_f32_e32 v64, v96
	v_exp_f32_e32 v65, v97
	v_exp_f32_e32 v66, v98
	v_exp_f32_e32 v67, v99
	v_exp_f32_e32 v68, v100
	v_exp_f32_e32 v69, v101
	v_exp_f32_e32 v70, v102
	s_waitcnt lgkmcnt(4)
	v_mfma_f32_32x32x16_bf16 v[16:31], v[156:159], v[182:185], v[16:31]
	v_exp_f32_e32 v71, v103
	v_exp_f32_e32 v72, v104
	v_exp_f32_e32 v73, v105
	v_exp_f32_e32 v74, v106
	v_exp_f32_e32 v75, v107
	v_exp_f32_e32 v76, v108
	v_exp_f32_e32 v77, v109
	s_waitcnt lgkmcnt(2)
	v_mfma_f32_32x32x16_bf16 v[16:31], v[112:115], v[206:209], v[16:31]
	v_exp_f32_e32 v78, v110
	v_exp_f32_e32 v79, v111
	s_waitcnt lgkmcnt(0)
	s_barrier
	ds_write_b128 v195, v[120:123] offset:16384
	ds_write_b128 v196, v[124:127] offset:16384
	v_mfma_f32_32x32x16_bf16 v[16:31], v[116:119], v[210:213], v[16:31]
	v_cmp_gt_f32_e32 vcc, 1.0, v180
	s_cbranch_vccz .LBB0_1724
	s_and_saveexec_b64 s[12:13], s[4:5]
	s_cbranch_execz .LBB0_1723
	ds_write_b32 v224, v180 offset:128
	s_branch .LBB0_1723
